# hand-written gated-branch GEMM epilogue (modes 1-3): rolling load window, f16 operands folded into fma_mix
# baseline (speedup 1.0000x reference)
.LBB0_386:
	s_andn2_b64 vcc, exec, s[10:11]
	s_cbranch_vccnz .LBB0_452
	v_add_u32_e32 v216, s1, v199
	v_or_b32_e32 v218, s4, v239
	v_mov_b64_e32 v[210:211], s[36:37]
	v_ashrrev_i32_e32 v219, 31, v218
	v_mad_i64_i32 v[210:211], s[10:11], v216, s55, v[210:211]
	v_ashrrev_i32_e32 v217, 31, v216
	s_mov_b64 s[2:3], 0x1000
	v_lshl_add_u64 v[210:211], v[204:205], 1, v[210:211]
	v_lshlrev_b64 v[212:213], 11, v[216:217]
	v_lshl_add_u64 v[210:211], v[218:219], 1, v[210:211]
	v_lshl_add_u64 v[212:213], s[34:35], 0, v[212:213]
	v_lshl_add_u64 v[210:211], v[210:211], 0, s[2:3]
	v_lshl_add_u64 v[212:213], v[218:219], 1, v[212:213]
	s_lshl_b32 s2, s55, 4
	s_mov_b32 s3, 0
	s_mul_i32 s56, s55, 0x50
	s_mov_b32 s57, 0
	s_mov_b64 s[10:11], 0x8000
	s_mov_b32 s5, 0xbfb8aa3b
	v_mov_b32_e32 v214, v212
	v_mov_b32_e32 v215, v213
	s_andn2_b64 vcc, exec, s[8:9]
	s_cbranch_vccnz .Lep13_noold
	s_mov_b64 vcc, 0x28000
	global_load_dwordx4 v[132:135], v[210:211], off
	global_load_dwordx4 v[136:139], v[210:211], off offset:256
	global_load_dwordx4 v[140:143], v[212:213], off
	global_load_dwordx4 v[144:147], v[212:213], off offset:256
	v_lshl_add_u64 v[210:211], v[210:211], 0, s[2:3]
	v_lshl_add_u64 v[212:213], v[212:213], 0, s[10:11]
	global_load_dwordx4 v[148:151], v[210:211], off
	global_load_dwordx4 v[152:155], v[210:211], off offset:256
	global_load_dwordx4 v[156:159], v[212:213], off
	global_load_dwordx4 v[160:163], v[212:213], off offset:256
	v_lshl_add_u64 v[210:211], v[210:211], 0, s[2:3]
	v_lshl_add_u64 v[212:213], v[212:213], 0, s[10:11]
	global_load_dwordx4 v[164:167], v[210:211], off
	global_load_dwordx4 v[168:171], v[210:211], off offset:256
	global_load_dwordx4 v[172:175], v[212:213], off
	global_load_dwordx4 v[176:179], v[212:213], off offset:256
	v_lshl_add_u64 v[210:211], v[210:211], 0, s[2:3]
	v_lshl_add_u64 v[212:213], v[212:213], 0, s[10:11]
	global_load_dwordx4 v[180:183], v[210:211], off
	global_load_dwordx4 v[184:187], v[210:211], off offset:256
	global_load_dwordx4 v[188:191], v[212:213], off
	global_load_dwordx4 v[192:195], v[212:213], off offset:256
	v_lshl_add_u64 v[210:211], v[210:211], 0, s[56:57]
	v_lshl_add_u64 v[212:213], v[212:213], 0, vcc
	s_waitcnt vmcnt(12)
	v_fma_mix_f32 v242, v132, s5, 0 op_sel:[0,0,0] op_sel_hi:[1,0,0]
	v_fma_mix_f32 v243, v132, s5, 0 op_sel:[1,0,0] op_sel_hi:[1,0,0]
	v_fma_mix_f32 v244, v133, s5, 0 op_sel:[0,0,0] op_sel_hi:[1,0,0]
	v_fma_mix_f32 v245, v133, s5, 0 op_sel:[1,0,0] op_sel_hi:[1,0,0]
	v_fma_mix_f32 v246, v134, s5, 0 op_sel:[0,0,0] op_sel_hi:[1,0,0]
	v_fma_mix_f32 v247, v134, s5, 0 op_sel:[1,0,0] op_sel_hi:[1,0,0]
	v_fma_mix_f32 v248, v135, s5, 0 op_sel:[0,0,0] op_sel_hi:[1,0,0]
	v_fma_mix_f32 v249, v135, s5, 0 op_sel:[1,0,0] op_sel_hi:[1,0,0]
	v_exp_f32_e32 v242, v242
	v_exp_f32_e32 v243, v243
	v_exp_f32_e32 v244, v244
	v_exp_f32_e32 v245, v245
	v_exp_f32_e32 v246, v246
	v_exp_f32_e32 v247, v247
	v_exp_f32_e32 v248, v248
	v_exp_f32_e32 v249, v249
	v_pk_add_f32 v[242:243], v[242:243], 1.0 op_sel_hi:[1,0]
	v_pk_add_f32 v[244:245], v[244:245], 1.0 op_sel_hi:[1,0]
	v_pk_add_f32 v[246:247], v[246:247], 1.0 op_sel_hi:[1,0]
	v_pk_add_f32 v[248:249], v[248:249], 1.0 op_sel_hi:[1,0]
	v_rcp_f32_e32 v242, v242
	v_rcp_f32_e32 v243, v243
	v_rcp_f32_e32 v244, v244
	v_rcp_f32_e32 v245, v245
	v_rcp_f32_e32 v246, v246
	v_rcp_f32_e32 v247, v247
	v_rcp_f32_e32 v248, v248
	v_rcp_f32_e32 v249, v249
	v_fma_mix_f32 v242, v124, v242, v140 op_sel:[0,0,0] op_sel_hi:[0,0,1]
	v_fma_mix_f32 v243, v125, v243, v140 op_sel:[0,0,1] op_sel_hi:[0,0,1]
	v_fma_mix_f32 v244, v126, v244, v141 op_sel:[0,0,0] op_sel_hi:[0,0,1]
	v_fma_mix_f32 v245, v127, v245, v141 op_sel:[0,0,1] op_sel_hi:[0,0,1]
	v_fma_mix_f32 v246, v128, v246, v142 op_sel:[0,0,0] op_sel_hi:[0,0,1]
	v_fma_mix_f32 v247, v129, v247, v142 op_sel:[0,0,1] op_sel_hi:[0,0,1]
	v_fma_mix_f32 v248, v130, v248, v143 op_sel:[0,0,0] op_sel_hi:[0,0,1]
	v_fma_mix_f32 v249, v131, v249, v143 op_sel:[0,0,1] op_sel_hi:[0,0,1]
	v_cvt_pk_f16_f32 v132, v242, v243
	v_cvt_pk_f16_f32 v133, v244, v245
	v_cvt_pk_f16_f32 v134, v246, v247
	v_cvt_pk_f16_f32 v135, v248, v249
	global_store_dwordx4 v[214:215], v[132:135], off
	v_fma_mix_f32 v242, v136, s5, 0 op_sel:[0,0,0] op_sel_hi:[1,0,0]
	v_fma_mix_f32 v243, v136, s5, 0 op_sel:[1,0,0] op_sel_hi:[1,0,0]
	v_fma_mix_f32 v244, v137, s5, 0 op_sel:[0,0,0] op_sel_hi:[1,0,0]
	v_fma_mix_f32 v245, v137, s5, 0 op_sel:[1,0,0] op_sel_hi:[1,0,0]
	v_fma_mix_f32 v246, v138, s5, 0 op_sel:[0,0,0] op_sel_hi:[1,0,0]
	v_fma_mix_f32 v247, v138, s5, 0 op_sel:[1,0,0] op_sel_hi:[1,0,0]
	v_fma_mix_f32 v248, v139, s5, 0 op_sel:[0,0,0] op_sel_hi:[1,0,0]
	v_fma_mix_f32 v249, v139, s5, 0 op_sel:[1,0,0] op_sel_hi:[1,0,0]
	v_exp_f32_e32 v242, v242
	v_exp_f32_e32 v243, v243
	v_exp_f32_e32 v244, v244
	v_exp_f32_e32 v245, v245
	v_exp_f32_e32 v246, v246
	v_exp_f32_e32 v247, v247
	v_exp_f32_e32 v248, v248
	v_exp_f32_e32 v249, v249
	v_pk_add_f32 v[242:243], v[242:243], 1.0 op_sel_hi:[1,0]
	v_pk_add_f32 v[244:245], v[244:245], 1.0 op_sel_hi:[1,0]
	v_pk_add_f32 v[246:247], v[246:247], 1.0 op_sel_hi:[1,0]
	v_pk_add_f32 v[248:249], v[248:249], 1.0 op_sel_hi:[1,0]
	v_rcp_f32_e32 v242, v242
	v_rcp_f32_e32 v243, v243
	v_rcp_f32_e32 v244, v244
	v_rcp_f32_e32 v245, v245
	v_rcp_f32_e32 v246, v246
	v_rcp_f32_e32 v247, v247
	v_rcp_f32_e32 v248, v248
	v_rcp_f32_e32 v249, v249
	v_fma_mix_f32 v242, v116, v242, v144 op_sel:[0,0,0] op_sel_hi:[0,0,1]
	v_fma_mix_f32 v243, v117, v243, v144 op_sel:[0,0,1] op_sel_hi:[0,0,1]
	v_fma_mix_f32 v244, v118, v244, v145 op_sel:[0,0,0] op_sel_hi:[0,0,1]
	v_fma_mix_f32 v245, v119, v245, v145 op_sel:[0,0,1] op_sel_hi:[0,0,1]
	v_fma_mix_f32 v246, v120, v246, v146 op_sel:[0,0,0] op_sel_hi:[0,0,1]
	v_fma_mix_f32 v247, v121, v247, v146 op_sel:[0,0,1] op_sel_hi:[0,0,1]
	v_fma_mix_f32 v248, v122, v248, v147 op_sel:[0,0,0] op_sel_hi:[0,0,1]
	v_fma_mix_f32 v249, v123, v249, v147 op_sel:[0,0,1] op_sel_hi:[0,0,1]
	v_cvt_pk_f16_f32 v136, v242, v243
	v_cvt_pk_f16_f32 v137, v244, v245
	v_cvt_pk_f16_f32 v138, v246, v247
	v_cvt_pk_f16_f32 v139, v248, v249
	global_store_dwordx4 v[214:215], v[136:139], off offset:256
	v_lshl_add_u64 v[214:215], v[214:215], 0, s[10:11]
	global_load_dwordx4 v[132:135], v[210:211], off
	global_load_dwordx4 v[136:139], v[210:211], off offset:256
	global_load_dwordx4 v[140:143], v[212:213], off
	global_load_dwordx4 v[144:147], v[212:213], off offset:256
	v_lshl_add_u64 v[210:211], v[210:211], 0, s[2:3]
	v_lshl_add_u64 v[212:213], v[212:213], 0, s[10:11]
	s_waitcnt vmcnt(14)
	v_fma_mix_f32 v242, v148, s5, 0 op_sel:[0,0,0] op_sel_hi:[1,0,0]
	v_fma_mix_f32 v243, v148, s5, 0 op_sel:[1,0,0] op_sel_hi:[1,0,0]
	v_fma_mix_f32 v244, v149, s5, 0 op_sel:[0,0,0] op_sel_hi:[1,0,0]
	v_fma_mix_f32 v245, v149, s5, 0 op_sel:[1,0,0] op_sel_hi:[1,0,0]
	v_fma_mix_f32 v246, v150, s5, 0 op_sel:[0,0,0] op_sel_hi:[1,0,0]
	v_fma_mix_f32 v247, v150, s5, 0 op_sel:[1,0,0] op_sel_hi:[1,0,0]
	v_fma_mix_f32 v248, v151, s5, 0 op_sel:[0,0,0] op_sel_hi:[1,0,0]
	v_fma_mix_f32 v249, v151, s5, 0 op_sel:[1,0,0] op_sel_hi:[1,0,0]
	v_exp_f32_e32 v242, v242
	v_exp_f32_e32 v243, v243
	v_exp_f32_e32 v244, v244
	v_exp_f32_e32 v245, v245
	v_exp_f32_e32 v246, v246
	v_exp_f32_e32 v247, v247
	v_exp_f32_e32 v248, v248
	v_exp_f32_e32 v249, v249
	v_pk_add_f32 v[242:243], v[242:243], 1.0 op_sel_hi:[1,0]
	v_pk_add_f32 v[244:245], v[244:245], 1.0 op_sel_hi:[1,0]
	v_pk_add_f32 v[246:247], v[246:247], 1.0 op_sel_hi:[1,0]
	v_pk_add_f32 v[248:249], v[248:249], 1.0 op_sel_hi:[1,0]
	v_rcp_f32_e32 v242, v242
	v_rcp_f32_e32 v243, v243
	v_rcp_f32_e32 v244, v244
	v_rcp_f32_e32 v245, v245
	v_rcp_f32_e32 v246, v246
	v_rcp_f32_e32 v247, v247
	v_rcp_f32_e32 v248, v248
	v_rcp_f32_e32 v249, v249
	v_fma_mix_f32 v242, v108, v242, v156 op_sel:[0,0,0] op_sel_hi:[0,0,1]
	v_fma_mix_f32 v243, v109, v243, v156 op_sel:[0,0,1] op_sel_hi:[0,0,1]
	v_fma_mix_f32 v244, v110, v244, v157 op_sel:[0,0,0] op_sel_hi:[0,0,1]
	v_fma_mix_f32 v245, v111, v245, v157 op_sel:[0,0,1] op_sel_hi:[0,0,1]
	v_fma_mix_f32 v246, v112, v246, v158 op_sel:[0,0,0] op_sel_hi:[0,0,1]
	v_fma_mix_f32 v247, v113, v247, v158 op_sel:[0,0,1] op_sel_hi:[0,0,1]
	v_fma_mix_f32 v248, v114, v248, v159 op_sel:[0,0,0] op_sel_hi:[0,0,1]
	v_fma_mix_f32 v249, v115, v249, v159 op_sel:[0,0,1] op_sel_hi:[0,0,1]
	v_cvt_pk_f16_f32 v148, v242, v243
	v_cvt_pk_f16_f32 v149, v244, v245
	v_cvt_pk_f16_f32 v150, v246, v247
	v_cvt_pk_f16_f32 v151, v248, v249
	global_store_dwordx4 v[214:215], v[148:151], off
	v_fma_mix_f32 v242, v152, s5, 0 op_sel:[0,0,0] op_sel_hi:[1,0,0]
	v_fma_mix_f32 v243, v152, s5, 0 op_sel:[1,0,0] op_sel_hi:[1,0,0]
	v_fma_mix_f32 v244, v153, s5, 0 op_sel:[0,0,0] op_sel_hi:[1,0,0]
	v_fma_mix_f32 v245, v153, s5, 0 op_sel:[1,0,0] op_sel_hi:[1,0,0]
	v_fma_mix_f32 v246, v154, s5, 0 op_sel:[0,0,0] op_sel_hi:[1,0,0]
	v_fma_mix_f32 v247, v154, s5, 0 op_sel:[1,0,0] op_sel_hi:[1,0,0]
	v_fma_mix_f32 v248, v155, s5, 0 op_sel:[0,0,0] op_sel_hi:[1,0,0]
	v_fma_mix_f32 v249, v155, s5, 0 op_sel:[1,0,0] op_sel_hi:[1,0,0]
	v_exp_f32_e32 v242, v242
	v_exp_f32_e32 v243, v243
	v_exp_f32_e32 v244, v244
	v_exp_f32_e32 v245, v245
	v_exp_f32_e32 v246, v246
	v_exp_f32_e32 v247, v247
	v_exp_f32_e32 v248, v248
	v_exp_f32_e32 v249, v249
	v_pk_add_f32 v[242:243], v[242:243], 1.0 op_sel_hi:[1,0]
	v_pk_add_f32 v[244:245], v[244:245], 1.0 op_sel_hi:[1,0]
	v_pk_add_f32 v[246:247], v[246:247], 1.0 op_sel_hi:[1,0]
	v_pk_add_f32 v[248:249], v[248:249], 1.0 op_sel_hi:[1,0]
	v_rcp_f32_e32 v242, v242
	v_rcp_f32_e32 v243, v243
	v_rcp_f32_e32 v244, v244
	v_rcp_f32_e32 v245, v245
	v_rcp_f32_e32 v246, v246
	v_rcp_f32_e32 v247, v247
	v_rcp_f32_e32 v248, v248
	v_rcp_f32_e32 v249, v249
	v_fma_mix_f32 v242, v100, v242, v160 op_sel:[0,0,0] op_sel_hi:[0,0,1]
	v_fma_mix_f32 v243, v101, v243, v160 op_sel:[0,0,1] op_sel_hi:[0,0,1]
	v_fma_mix_f32 v244, v102, v244, v161 op_sel:[0,0,0] op_sel_hi:[0,0,1]
	v_fma_mix_f32 v245, v103, v245, v161 op_sel:[0,0,1] op_sel_hi:[0,0,1]
	v_fma_mix_f32 v246, v104, v246, v162 op_sel:[0,0,0] op_sel_hi:[0,0,1]
	v_fma_mix_f32 v247, v105, v247, v162 op_sel:[0,0,1] op_sel_hi:[0,0,1]
	v_fma_mix_f32 v248, v106, v248, v163 op_sel:[0,0,0] op_sel_hi:[0,0,1]
	v_fma_mix_f32 v249, v107, v249, v163 op_sel:[0,0,1] op_sel_hi:[0,0,1]
	v_cvt_pk_f16_f32 v152, v242, v243
	v_cvt_pk_f16_f32 v153, v244, v245
	v_cvt_pk_f16_f32 v154, v246, v247
	v_cvt_pk_f16_f32 v155, v248, v249
	global_store_dwordx4 v[214:215], v[152:155], off offset:256
	v_lshl_add_u64 v[214:215], v[214:215], 0, s[10:11]
	global_load_dwordx4 v[148:151], v[210:211], off
	global_load_dwordx4 v[152:155], v[210:211], off offset:256
	global_load_dwordx4 v[156:159], v[212:213], off
	global_load_dwordx4 v[160:163], v[212:213], off offset:256
	v_lshl_add_u64 v[210:211], v[210:211], 0, s[2:3]
	v_lshl_add_u64 v[212:213], v[212:213], 0, s[10:11]
	s_waitcnt vmcnt(16)
	v_fma_mix_f32 v242, v164, s5, 0 op_sel:[0,0,0] op_sel_hi:[1,0,0]
	v_fma_mix_f32 v243, v164, s5, 0 op_sel:[1,0,0] op_sel_hi:[1,0,0]
	v_fma_mix_f32 v244, v165, s5, 0 op_sel:[0,0,0] op_sel_hi:[1,0,0]
	v_fma_mix_f32 v245, v165, s5, 0 op_sel:[1,0,0] op_sel_hi:[1,0,0]
	v_fma_mix_f32 v246, v166, s5, 0 op_sel:[0,0,0] op_sel_hi:[1,0,0]
	v_fma_mix_f32 v247, v166, s5, 0 op_sel:[1,0,0] op_sel_hi:[1,0,0]
	v_fma_mix_f32 v248, v167, s5, 0 op_sel:[0,0,0] op_sel_hi:[1,0,0]
	v_fma_mix_f32 v249, v167, s5, 0 op_sel:[1,0,0] op_sel_hi:[1,0,0]
	v_exp_f32_e32 v242, v242
	v_exp_f32_e32 v243, v243
	v_exp_f32_e32 v244, v244
	v_exp_f32_e32 v245, v245
	v_exp_f32_e32 v246, v246
	v_exp_f32_e32 v247, v247
	v_exp_f32_e32 v248, v248
	v_exp_f32_e32 v249, v249
	v_pk_add_f32 v[242:243], v[242:243], 1.0 op_sel_hi:[1,0]
	v_pk_add_f32 v[244:245], v[244:245], 1.0 op_sel_hi:[1,0]
	v_pk_add_f32 v[246:247], v[246:247], 1.0 op_sel_hi:[1,0]
	v_pk_add_f32 v[248:249], v[248:249], 1.0 op_sel_hi:[1,0]
	v_rcp_f32_e32 v242, v242
	v_rcp_f32_e32 v243, v243
	v_rcp_f32_e32 v244, v244
	v_rcp_f32_e32 v245, v245
	v_rcp_f32_e32 v246, v246
	v_rcp_f32_e32 v247, v247
	v_rcp_f32_e32 v248, v248
	v_rcp_f32_e32 v249, v249
	v_fma_mix_f32 v242, v92, v242, v172 op_sel:[0,0,0] op_sel_hi:[0,0,1]
	v_fma_mix_f32 v243, v93, v243, v172 op_sel:[0,0,1] op_sel_hi:[0,0,1]
	v_fma_mix_f32 v244, v94, v244, v173 op_sel:[0,0,0] op_sel_hi:[0,0,1]
	v_fma_mix_f32 v245, v95, v245, v173 op_sel:[0,0,1] op_sel_hi:[0,0,1]
	v_fma_mix_f32 v246, v96, v246, v174 op_sel:[0,0,0] op_sel_hi:[0,0,1]
	v_fma_mix_f32 v247, v97, v247, v174 op_sel:[0,0,1] op_sel_hi:[0,0,1]
	v_fma_mix_f32 v248, v98, v248, v175 op_sel:[0,0,0] op_sel_hi:[0,0,1]
	v_fma_mix_f32 v249, v99, v249, v175 op_sel:[0,0,1] op_sel_hi:[0,0,1]
	v_cvt_pk_f16_f32 v164, v242, v243
	v_cvt_pk_f16_f32 v165, v244, v245
	v_cvt_pk_f16_f32 v166, v246, v247
	v_cvt_pk_f16_f32 v167, v248, v249
	global_store_dwordx4 v[214:215], v[164:167], off
	v_fma_mix_f32 v242, v168, s5, 0 op_sel:[0,0,0] op_sel_hi:[1,0,0]
	v_fma_mix_f32 v243, v168, s5, 0 op_sel:[1,0,0] op_sel_hi:[1,0,0]
	v_fma_mix_f32 v244, v169, s5, 0 op_sel:[0,0,0] op_sel_hi:[1,0,0]
	v_fma_mix_f32 v245, v169, s5, 0 op_sel:[1,0,0] op_sel_hi:[1,0,0]
	v_fma_mix_f32 v246, v170, s5, 0 op_sel:[0,0,0] op_sel_hi:[1,0,0]
	v_fma_mix_f32 v247, v170, s5, 0 op_sel:[1,0,0] op_sel_hi:[1,0,0]
	v_fma_mix_f32 v248, v171, s5, 0 op_sel:[0,0,0] op_sel_hi:[1,0,0]
	v_fma_mix_f32 v249, v171, s5, 0 op_sel:[1,0,0] op_sel_hi:[1,0,0]
	v_exp_f32_e32 v242, v242
	v_exp_f32_e32 v243, v243
	v_exp_f32_e32 v244, v244
	v_exp_f32_e32 v245, v245
	v_exp_f32_e32 v246, v246
	v_exp_f32_e32 v247, v247
	v_exp_f32_e32 v248, v248
	v_exp_f32_e32 v249, v249
	v_pk_add_f32 v[242:243], v[242:243], 1.0 op_sel_hi:[1,0]
	v_pk_add_f32 v[244:245], v[244:245], 1.0 op_sel_hi:[1,0]
	v_pk_add_f32 v[246:247], v[246:247], 1.0 op_sel_hi:[1,0]
	v_pk_add_f32 v[248:249], v[248:249], 1.0 op_sel_hi:[1,0]
	v_rcp_f32_e32 v242, v242
	v_rcp_f32_e32 v243, v243
	v_rcp_f32_e32 v244, v244
	v_rcp_f32_e32 v245, v245
	v_rcp_f32_e32 v246, v246
	v_rcp_f32_e32 v247, v247
	v_rcp_f32_e32 v248, v248
	v_rcp_f32_e32 v249, v249
	v_fma_mix_f32 v242, v84, v242, v176 op_sel:[0,0,0] op_sel_hi:[0,0,1]
	v_fma_mix_f32 v243, v85, v243, v176 op_sel:[0,0,1] op_sel_hi:[0,0,1]
	v_fma_mix_f32 v244, v86, v244, v177 op_sel:[0,0,0] op_sel_hi:[0,0,1]
	v_fma_mix_f32 v245, v87, v245, v177 op_sel:[0,0,1] op_sel_hi:[0,0,1]
	v_fma_mix_f32 v246, v88, v246, v178 op_sel:[0,0,0] op_sel_hi:[0,0,1]
	v_fma_mix_f32 v247, v89, v247, v178 op_sel:[0,0,1] op_sel_hi:[0,0,1]
	v_fma_mix_f32 v248, v90, v248, v179 op_sel:[0,0,0] op_sel_hi:[0,0,1]
	v_fma_mix_f32 v249, v91, v249, v179 op_sel:[0,0,1] op_sel_hi:[0,0,1]
	v_cvt_pk_f16_f32 v168, v242, v243
	v_cvt_pk_f16_f32 v169, v244, v245
	v_cvt_pk_f16_f32 v170, v246, v247
	v_cvt_pk_f16_f32 v171, v248, v249
	global_store_dwordx4 v[214:215], v[168:171], off offset:256
	v_lshl_add_u64 v[214:215], v[214:215], 0, s[10:11]
	global_load_dwordx4 v[164:167], v[210:211], off
	global_load_dwordx4 v[168:171], v[210:211], off offset:256
	global_load_dwordx4 v[172:175], v[212:213], off
	global_load_dwordx4 v[176:179], v[212:213], off offset:256
	v_lshl_add_u64 v[210:211], v[210:211], 0, s[2:3]
	v_lshl_add_u64 v[212:213], v[212:213], 0, s[10:11]
	s_waitcnt vmcnt(18)
	v_fma_mix_f32 v242, v180, s5, 0 op_sel:[0,0,0] op_sel_hi:[1,0,0]
	v_fma_mix_f32 v243, v180, s5, 0 op_sel:[1,0,0] op_sel_hi:[1,0,0]
	v_fma_mix_f32 v244, v181, s5, 0 op_sel:[0,0,0] op_sel_hi:[1,0,0]
	v_fma_mix_f32 v245, v181, s5, 0 op_sel:[1,0,0] op_sel_hi:[1,0,0]
	v_fma_mix_f32 v246, v182, s5, 0 op_sel:[0,0,0] op_sel_hi:[1,0,0]
	v_fma_mix_f32 v247, v182, s5, 0 op_sel:[1,0,0] op_sel_hi:[1,0,0]
	v_fma_mix_f32 v248, v183, s5, 0 op_sel:[0,0,0] op_sel_hi:[1,0,0]
	v_fma_mix_f32 v249, v183, s5, 0 op_sel:[1,0,0] op_sel_hi:[1,0,0]
	v_exp_f32_e32 v242, v242
	v_exp_f32_e32 v243, v243
	v_exp_f32_e32 v244, v244
	v_exp_f32_e32 v245, v245
	v_exp_f32_e32 v246, v246
	v_exp_f32_e32 v247, v247
	v_exp_f32_e32 v248, v248
	v_exp_f32_e32 v249, v249
	v_pk_add_f32 v[242:243], v[242:243], 1.0 op_sel_hi:[1,0]
	v_pk_add_f32 v[244:245], v[244:245], 1.0 op_sel_hi:[1,0]
	v_pk_add_f32 v[246:247], v[246:247], 1.0 op_sel_hi:[1,0]
	v_pk_add_f32 v[248:249], v[248:249], 1.0 op_sel_hi:[1,0]
	v_rcp_f32_e32 v242, v242
	v_rcp_f32_e32 v243, v243
	v_rcp_f32_e32 v244, v244
	v_rcp_f32_e32 v245, v245
	v_rcp_f32_e32 v246, v246
	v_rcp_f32_e32 v247, v247
	v_rcp_f32_e32 v248, v248
	v_rcp_f32_e32 v249, v249
	v_fma_mix_f32 v242, v76, v242, v188 op_sel:[0,0,0] op_sel_hi:[0,0,1]
	v_fma_mix_f32 v243, v77, v243, v188 op_sel:[0,0,1] op_sel_hi:[0,0,1]
	v_fma_mix_f32 v244, v78, v244, v189 op_sel:[0,0,0] op_sel_hi:[0,0,1]
	v_fma_mix_f32 v245, v79, v245, v189 op_sel:[0,0,1] op_sel_hi:[0,0,1]
	v_fma_mix_f32 v246, v80, v246, v190 op_sel:[0,0,0] op_sel_hi:[0,0,1]
	v_fma_mix_f32 v247, v81, v247, v190 op_sel:[0,0,1] op_sel_hi:[0,0,1]
	v_fma_mix_f32 v248, v82, v248, v191 op_sel:[0,0,0] op_sel_hi:[0,0,1]
	v_fma_mix_f32 v249, v83, v249, v191 op_sel:[0,0,1] op_sel_hi:[0,0,1]
	v_cvt_pk_f16_f32 v180, v242, v243
	v_cvt_pk_f16_f32 v181, v244, v245
	v_cvt_pk_f16_f32 v182, v246, v247
	v_cvt_pk_f16_f32 v183, v248, v249
	global_store_dwordx4 v[214:215], v[180:183], off
	v_fma_mix_f32 v242, v184, s5, 0 op_sel:[0,0,0] op_sel_hi:[1,0,0]
	v_fma_mix_f32 v243, v184, s5, 0 op_sel:[1,0,0] op_sel_hi:[1,0,0]
	v_fma_mix_f32 v244, v185, s5, 0 op_sel:[0,0,0] op_sel_hi:[1,0,0]
	v_fma_mix_f32 v245, v185, s5, 0 op_sel:[1,0,0] op_sel_hi:[1,0,0]
	v_fma_mix_f32 v246, v186, s5, 0 op_sel:[0,0,0] op_sel_hi:[1,0,0]
	v_fma_mix_f32 v247, v186, s5, 0 op_sel:[1,0,0] op_sel_hi:[1,0,0]
	v_fma_mix_f32 v248, v187, s5, 0 op_sel:[0,0,0] op_sel_hi:[1,0,0]
	v_fma_mix_f32 v249, v187, s5, 0 op_sel:[1,0,0] op_sel_hi:[1,0,0]
	v_exp_f32_e32 v242, v242
	v_exp_f32_e32 v243, v243
	v_exp_f32_e32 v244, v244
	v_exp_f32_e32 v245, v245
	v_exp_f32_e32 v246, v246
	v_exp_f32_e32 v247, v247
	v_exp_f32_e32 v248, v248
	v_exp_f32_e32 v249, v249
	v_pk_add_f32 v[242:243], v[242:243], 1.0 op_sel_hi:[1,0]
	v_pk_add_f32 v[244:245], v[244:245], 1.0 op_sel_hi:[1,0]
	v_pk_add_f32 v[246:247], v[246:247], 1.0 op_sel_hi:[1,0]
	v_pk_add_f32 v[248:249], v[248:249], 1.0 op_sel_hi:[1,0]
	v_rcp_f32_e32 v242, v242
	v_rcp_f32_e32 v243, v243
	v_rcp_f32_e32 v244, v244
	v_rcp_f32_e32 v245, v245
	v_rcp_f32_e32 v246, v246
	v_rcp_f32_e32 v247, v247
	v_rcp_f32_e32 v248, v248
	v_rcp_f32_e32 v249, v249
	v_fma_mix_f32 v242, v68, v242, v192 op_sel:[0,0,0] op_sel_hi:[0,0,1]
	v_fma_mix_f32 v243, v69, v243, v192 op_sel:[0,0,1] op_sel_hi:[0,0,1]
	v_fma_mix_f32 v244, v70, v244, v193 op_sel:[0,0,0] op_sel_hi:[0,0,1]
	v_fma_mix_f32 v245, v71, v245, v193 op_sel:[0,0,1] op_sel_hi:[0,0,1]
	v_fma_mix_f32 v246, v72, v246, v194 op_sel:[0,0,0] op_sel_hi:[0,0,1]
	v_fma_mix_f32 v247, v73, v247, v194 op_sel:[0,0,1] op_sel_hi:[0,0,1]
	v_fma_mix_f32 v248, v74, v248, v195 op_sel:[0,0,0] op_sel_hi:[0,0,1]
	v_fma_mix_f32 v249, v75, v249, v195 op_sel:[0,0,1] op_sel_hi:[0,0,1]
	v_cvt_pk_f16_f32 v184, v242, v243
	v_cvt_pk_f16_f32 v185, v244, v245
	v_cvt_pk_f16_f32 v186, v246, v247
	v_cvt_pk_f16_f32 v187, v248, v249
	global_store_dwordx4 v[214:215], v[184:187], off offset:256
	v_lshl_add_u64 v[214:215], v[214:215], 0, vcc
	global_load_dwordx4 v[180:183], v[210:211], off
	global_load_dwordx4 v[184:187], v[210:211], off offset:256
	global_load_dwordx4 v[188:191], v[212:213], off
	global_load_dwordx4 v[192:195], v[212:213], off offset:256
	s_waitcnt vmcnt(18)
	v_fma_mix_f32 v242, v132, s5, 0 op_sel:[0,0,0] op_sel_hi:[1,0,0]
	v_fma_mix_f32 v243, v132, s5, 0 op_sel:[1,0,0] op_sel_hi:[1,0,0]
	v_fma_mix_f32 v244, v133, s5, 0 op_sel:[0,0,0] op_sel_hi:[1,0,0]
	v_fma_mix_f32 v245, v133, s5, 0 op_sel:[1,0,0] op_sel_hi:[1,0,0]
	v_fma_mix_f32 v246, v134, s5, 0 op_sel:[0,0,0] op_sel_hi:[1,0,0]
	v_fma_mix_f32 v247, v134, s5, 0 op_sel:[1,0,0] op_sel_hi:[1,0,0]
	v_fma_mix_f32 v248, v135, s5, 0 op_sel:[0,0,0] op_sel_hi:[1,0,0]
	v_fma_mix_f32 v249, v135, s5, 0 op_sel:[1,0,0] op_sel_hi:[1,0,0]
	v_exp_f32_e32 v242, v242
	v_exp_f32_e32 v243, v243
	v_exp_f32_e32 v244, v244
	v_exp_f32_e32 v245, v245
	v_exp_f32_e32 v246, v246
	v_exp_f32_e32 v247, v247
	v_exp_f32_e32 v248, v248
	v_exp_f32_e32 v249, v249
	v_pk_add_f32 v[242:243], v[242:243], 1.0 op_sel_hi:[1,0]
	v_pk_add_f32 v[244:245], v[244:245], 1.0 op_sel_hi:[1,0]
	v_pk_add_f32 v[246:247], v[246:247], 1.0 op_sel_hi:[1,0]
	v_pk_add_f32 v[248:249], v[248:249], 1.0 op_sel_hi:[1,0]
	v_rcp_f32_e32 v242, v242
	v_rcp_f32_e32 v243, v243
	v_rcp_f32_e32 v244, v244
	v_rcp_f32_e32 v245, v245
	v_rcp_f32_e32 v246, v246
	v_rcp_f32_e32 v247, v247
	v_rcp_f32_e32 v248, v248
	v_rcp_f32_e32 v249, v249
	v_fma_mix_f32 v242, v60, v242, v140 op_sel:[0,0,0] op_sel_hi:[0,0,1]
	v_fma_mix_f32 v243, v61, v243, v140 op_sel:[0,0,1] op_sel_hi:[0,0,1]
	v_fma_mix_f32 v244, v62, v244, v141 op_sel:[0,0,0] op_sel_hi:[0,0,1]
	v_fma_mix_f32 v245, v63, v245, v141 op_sel:[0,0,1] op_sel_hi:[0,0,1]
	v_fma_mix_f32 v246, v64, v246, v142 op_sel:[0,0,0] op_sel_hi:[0,0,1]
	v_fma_mix_f32 v247, v65, v247, v142 op_sel:[0,0,1] op_sel_hi:[0,0,1]
	v_fma_mix_f32 v248, v66, v248, v143 op_sel:[0,0,0] op_sel_hi:[0,0,1]
	v_fma_mix_f32 v249, v67, v249, v143 op_sel:[0,0,1] op_sel_hi:[0,0,1]
	v_cvt_pk_f16_f32 v132, v242, v243
	v_cvt_pk_f16_f32 v133, v244, v245
	v_cvt_pk_f16_f32 v134, v246, v247
	v_cvt_pk_f16_f32 v135, v248, v249
	global_store_dwordx4 v[214:215], v[132:135], off
	v_fma_mix_f32 v242, v136, s5, 0 op_sel:[0,0,0] op_sel_hi:[1,0,0]
	v_fma_mix_f32 v243, v136, s5, 0 op_sel:[1,0,0] op_sel_hi:[1,0,0]
	v_fma_mix_f32 v244, v137, s5, 0 op_sel:[0,0,0] op_sel_hi:[1,0,0]
	v_fma_mix_f32 v245, v137, s5, 0 op_sel:[1,0,0] op_sel_hi:[1,0,0]
	v_fma_mix_f32 v246, v138, s5, 0 op_sel:[0,0,0] op_sel_hi:[1,0,0]
	v_fma_mix_f32 v247, v138, s5, 0 op_sel:[1,0,0] op_sel_hi:[1,0,0]
	v_fma_mix_f32 v248, v139, s5, 0 op_sel:[0,0,0] op_sel_hi:[1,0,0]
	v_fma_mix_f32 v249, v139, s5, 0 op_sel:[1,0,0] op_sel_hi:[1,0,0]
	v_exp_f32_e32 v242, v242
	v_exp_f32_e32 v243, v243
	v_exp_f32_e32 v244, v244
	v_exp_f32_e32 v245, v245
	v_exp_f32_e32 v246, v246
	v_exp_f32_e32 v247, v247
	v_exp_f32_e32 v248, v248
	v_exp_f32_e32 v249, v249
	v_pk_add_f32 v[242:243], v[242:243], 1.0 op_sel_hi:[1,0]
	v_pk_add_f32 v[244:245], v[244:245], 1.0 op_sel_hi:[1,0]
	v_pk_add_f32 v[246:247], v[246:247], 1.0 op_sel_hi:[1,0]
	v_pk_add_f32 v[248:249], v[248:249], 1.0 op_sel_hi:[1,0]
	v_rcp_f32_e32 v242, v242
	v_rcp_f32_e32 v243, v243
	v_rcp_f32_e32 v244, v244
	v_rcp_f32_e32 v245, v245
	v_rcp_f32_e32 v246, v246
	v_rcp_f32_e32 v247, v247
	v_rcp_f32_e32 v248, v248
	v_rcp_f32_e32 v249, v249
	v_fma_mix_f32 v242, v52, v242, v144 op_sel:[0,0,0] op_sel_hi:[0,0,1]
	v_fma_mix_f32 v243, v53, v243, v144 op_sel:[0,0,1] op_sel_hi:[0,0,1]
	v_fma_mix_f32 v244, v54, v244, v145 op_sel:[0,0,0] op_sel_hi:[0,0,1]
	v_fma_mix_f32 v245, v55, v245, v145 op_sel:[0,0,1] op_sel_hi:[0,0,1]
	v_fma_mix_f32 v246, v56, v246, v146 op_sel:[0,0,0] op_sel_hi:[0,0,1]
	v_fma_mix_f32 v247, v57, v247, v146 op_sel:[0,0,1] op_sel_hi:[0,0,1]
	v_fma_mix_f32 v248, v58, v248, v147 op_sel:[0,0,0] op_sel_hi:[0,0,1]
	v_fma_mix_f32 v249, v59, v249, v147 op_sel:[0,0,1] op_sel_hi:[0,0,1]
	v_cvt_pk_f16_f32 v136, v242, v243
	v_cvt_pk_f16_f32 v137, v244, v245
	v_cvt_pk_f16_f32 v138, v246, v247
	v_cvt_pk_f16_f32 v139, v248, v249
	global_store_dwordx4 v[214:215], v[136:139], off offset:256
	v_lshl_add_u64 v[214:215], v[214:215], 0, s[10:11]
	s_waitcnt vmcnt(14)
	v_fma_mix_f32 v242, v148, s5, 0 op_sel:[0,0,0] op_sel_hi:[1,0,0]
	v_fma_mix_f32 v243, v148, s5, 0 op_sel:[1,0,0] op_sel_hi:[1,0,0]
	v_fma_mix_f32 v244, v149, s5, 0 op_sel:[0,0,0] op_sel_hi:[1,0,0]
	v_fma_mix_f32 v245, v149, s5, 0 op_sel:[1,0,0] op_sel_hi:[1,0,0]
	v_fma_mix_f32 v246, v150, s5, 0 op_sel:[0,0,0] op_sel_hi:[1,0,0]
	v_fma_mix_f32 v247, v150, s5, 0 op_sel:[1,0,0] op_sel_hi:[1,0,0]
	v_fma_mix_f32 v248, v151, s5, 0 op_sel:[0,0,0] op_sel_hi:[1,0,0]
	v_fma_mix_f32 v249, v151, s5, 0 op_sel:[1,0,0] op_sel_hi:[1,0,0]
	v_exp_f32_e32 v242, v242
	v_exp_f32_e32 v243, v243
	v_exp_f32_e32 v244, v244
	v_exp_f32_e32 v245, v245
	v_exp_f32_e32 v246, v246
	v_exp_f32_e32 v247, v247
	v_exp_f32_e32 v248, v248
	v_exp_f32_e32 v249, v249
	v_pk_add_f32 v[242:243], v[242:243], 1.0 op_sel_hi:[1,0]
	v_pk_add_f32 v[244:245], v[244:245], 1.0 op_sel_hi:[1,0]
	v_pk_add_f32 v[246:247], v[246:247], 1.0 op_sel_hi:[1,0]
	v_pk_add_f32 v[248:249], v[248:249], 1.0 op_sel_hi:[1,0]
	v_rcp_f32_e32 v242, v242
	v_rcp_f32_e32 v243, v243
	v_rcp_f32_e32 v244, v244
	v_rcp_f32_e32 v245, v245
	v_rcp_f32_e32 v246, v246
	v_rcp_f32_e32 v247, v247
	v_rcp_f32_e32 v248, v248
	v_rcp_f32_e32 v249, v249
	v_fma_mix_f32 v242, v44, v242, v156 op_sel:[0,0,0] op_sel_hi:[0,0,1]
	v_fma_mix_f32 v243, v45, v243, v156 op_sel:[0,0,1] op_sel_hi:[0,0,1]
	v_fma_mix_f32 v244, v46, v244, v157 op_sel:[0,0,0] op_sel_hi:[0,0,1]
	v_fma_mix_f32 v245, v47, v245, v157 op_sel:[0,0,1] op_sel_hi:[0,0,1]
	v_fma_mix_f32 v246, v48, v246, v158 op_sel:[0,0,0] op_sel_hi:[0,0,1]
	v_fma_mix_f32 v247, v49, v247, v158 op_sel:[0,0,1] op_sel_hi:[0,0,1]
	v_fma_mix_f32 v248, v50, v248, v159 op_sel:[0,0,0] op_sel_hi:[0,0,1]
	v_fma_mix_f32 v249, v51, v249, v159 op_sel:[0,0,1] op_sel_hi:[0,0,1]
	v_cvt_pk_f16_f32 v148, v242, v243
	v_cvt_pk_f16_f32 v149, v244, v245
	v_cvt_pk_f16_f32 v150, v246, v247
	v_cvt_pk_f16_f32 v151, v248, v249
	global_store_dwordx4 v[214:215], v[148:151], off
	v_fma_mix_f32 v242, v152, s5, 0 op_sel:[0,0,0] op_sel_hi:[1,0,0]
	v_fma_mix_f32 v243, v152, s5, 0 op_sel:[1,0,0] op_sel_hi:[1,0,0]
	v_fma_mix_f32 v244, v153, s5, 0 op_sel:[0,0,0] op_sel_hi:[1,0,0]
	v_fma_mix_f32 v245, v153, s5, 0 op_sel:[1,0,0] op_sel_hi:[1,0,0]
	v_fma_mix_f32 v246, v154, s5, 0 op_sel:[0,0,0] op_sel_hi:[1,0,0]
	v_fma_mix_f32 v247, v154, s5, 0 op_sel:[1,0,0] op_sel_hi:[1,0,0]
	v_fma_mix_f32 v248, v155, s5, 0 op_sel:[0,0,0] op_sel_hi:[1,0,0]
	v_fma_mix_f32 v249, v155, s5, 0 op_sel:[1,0,0] op_sel_hi:[1,0,0]
	v_exp_f32_e32 v242, v242
	v_exp_f32_e32 v243, v243
	v_exp_f32_e32 v244, v244
	v_exp_f32_e32 v245, v245
	v_exp_f32_e32 v246, v246
	v_exp_f32_e32 v247, v247
	v_exp_f32_e32 v248, v248
	v_exp_f32_e32 v249, v249
	v_pk_add_f32 v[242:243], v[242:243], 1.0 op_sel_hi:[1,0]
	v_pk_add_f32 v[244:245], v[244:245], 1.0 op_sel_hi:[1,0]
	v_pk_add_f32 v[246:247], v[246:247], 1.0 op_sel_hi:[1,0]
	v_pk_add_f32 v[248:249], v[248:249], 1.0 op_sel_hi:[1,0]
	v_rcp_f32_e32 v242, v242
	v_rcp_f32_e32 v243, v243
	v_rcp_f32_e32 v244, v244
	v_rcp_f32_e32 v245, v245
	v_rcp_f32_e32 v246, v246
	v_rcp_f32_e32 v247, v247
	v_rcp_f32_e32 v248, v248
	v_rcp_f32_e32 v249, v249
	v_fma_mix_f32 v242, v36, v242, v160 op_sel:[0,0,0] op_sel_hi:[0,0,1]
	v_fma_mix_f32 v243, v37, v243, v160 op_sel:[0,0,1] op_sel_hi:[0,0,1]
	v_fma_mix_f32 v244, v38, v244, v161 op_sel:[0,0,0] op_sel_hi:[0,0,1]
	v_fma_mix_f32 v245, v39, v245, v161 op_sel:[0,0,1] op_sel_hi:[0,0,1]
	v_fma_mix_f32 v246, v40, v246, v162 op_sel:[0,0,0] op_sel_hi:[0,0,1]
	v_fma_mix_f32 v247, v41, v247, v162 op_sel:[0,0,1] op_sel_hi:[0,0,1]
	v_fma_mix_f32 v248, v42, v248, v163 op_sel:[0,0,0] op_sel_hi:[0,0,1]
	v_fma_mix_f32 v249, v43, v249, v163 op_sel:[0,0,1] op_sel_hi:[0,0,1]
	v_cvt_pk_f16_f32 v152, v242, v243
	v_cvt_pk_f16_f32 v153, v244, v245
	v_cvt_pk_f16_f32 v154, v246, v247
	v_cvt_pk_f16_f32 v155, v248, v249
	global_store_dwordx4 v[214:215], v[152:155], off offset:256
	v_lshl_add_u64 v[214:215], v[214:215], 0, s[10:11]
	s_waitcnt vmcnt(10)
	v_fma_mix_f32 v242, v164, s5, 0 op_sel:[0,0,0] op_sel_hi:[1,0,0]
	v_fma_mix_f32 v243, v164, s5, 0 op_sel:[1,0,0] op_sel_hi:[1,0,0]
	v_fma_mix_f32 v244, v165, s5, 0 op_sel:[0,0,0] op_sel_hi:[1,0,0]
	v_fma_mix_f32 v245, v165, s5, 0 op_sel:[1,0,0] op_sel_hi:[1,0,0]
	v_fma_mix_f32 v246, v166, s5, 0 op_sel:[0,0,0] op_sel_hi:[1,0,0]
	v_fma_mix_f32 v247, v166, s5, 0 op_sel:[1,0,0] op_sel_hi:[1,0,0]
	v_fma_mix_f32 v248, v167, s5, 0 op_sel:[0,0,0] op_sel_hi:[1,0,0]
	v_fma_mix_f32 v249, v167, s5, 0 op_sel:[1,0,0] op_sel_hi:[1,0,0]
	v_exp_f32_e32 v242, v242
	v_exp_f32_e32 v243, v243
	v_exp_f32_e32 v244, v244
	v_exp_f32_e32 v245, v245
	v_exp_f32_e32 v246, v246
	v_exp_f32_e32 v247, v247
	v_exp_f32_e32 v248, v248
	v_exp_f32_e32 v249, v249
	v_pk_add_f32 v[242:243], v[242:243], 1.0 op_sel_hi:[1,0]
	v_pk_add_f32 v[244:245], v[244:245], 1.0 op_sel_hi:[1,0]
	v_pk_add_f32 v[246:247], v[246:247], 1.0 op_sel_hi:[1,0]
	v_pk_add_f32 v[248:249], v[248:249], 1.0 op_sel_hi:[1,0]
	v_rcp_f32_e32 v242, v242
	v_rcp_f32_e32 v243, v243
	v_rcp_f32_e32 v244, v244
	v_rcp_f32_e32 v245, v245
	v_rcp_f32_e32 v246, v246
	v_rcp_f32_e32 v247, v247
	v_rcp_f32_e32 v248, v248
	v_rcp_f32_e32 v249, v249
	v_fma_mix_f32 v242, v28, v242, v172 op_sel:[0,0,0] op_sel_hi:[0,0,1]
	v_fma_mix_f32 v243, v29, v243, v172 op_sel:[0,0,1] op_sel_hi:[0,0,1]
	v_fma_mix_f32 v244, v30, v244, v173 op_sel:[0,0,0] op_sel_hi:[0,0,1]
	v_fma_mix_f32 v245, v31, v245, v173 op_sel:[0,0,1] op_sel_hi:[0,0,1]
	v_fma_mix_f32 v246, v32, v246, v174 op_sel:[0,0,0] op_sel_hi:[0,0,1]
	v_fma_mix_f32 v247, v33, v247, v174 op_sel:[0,0,1] op_sel_hi:[0,0,1]
	v_fma_mix_f32 v248, v34, v248, v175 op_sel:[0,0,0] op_sel_hi:[0,0,1]
	v_fma_mix_f32 v249, v35, v249, v175 op_sel:[0,0,1] op_sel_hi:[0,0,1]
	v_cvt_pk_f16_f32 v164, v242, v243
	v_cvt_pk_f16_f32 v165, v244, v245
	v_cvt_pk_f16_f32 v166, v246, v247
	v_cvt_pk_f16_f32 v167, v248, v249
	global_store_dwordx4 v[214:215], v[164:167], off
	v_fma_mix_f32 v242, v168, s5, 0 op_sel:[0,0,0] op_sel_hi:[1,0,0]
	v_fma_mix_f32 v243, v168, s5, 0 op_sel:[1,0,0] op_sel_hi:[1,0,0]
	v_fma_mix_f32 v244, v169, s5, 0 op_sel:[0,0,0] op_sel_hi:[1,0,0]
	v_fma_mix_f32 v245, v169, s5, 0 op_sel:[1,0,0] op_sel_hi:[1,0,0]
	v_fma_mix_f32 v246, v170, s5, 0 op_sel:[0,0,0] op_sel_hi:[1,0,0]
	v_fma_mix_f32 v247, v170, s5, 0 op_sel:[1,0,0] op_sel_hi:[1,0,0]
	v_fma_mix_f32 v248, v171, s5, 0 op_sel:[0,0,0] op_sel_hi:[1,0,0]
	v_fma_mix_f32 v249, v171, s5, 0 op_sel:[1,0,0] op_sel_hi:[1,0,0]
	v_exp_f32_e32 v242, v242
	v_exp_f32_e32 v243, v243
	v_exp_f32_e32 v244, v244
	v_exp_f32_e32 v245, v245
	v_exp_f32_e32 v246, v246
	v_exp_f32_e32 v247, v247
	v_exp_f32_e32 v248, v248
	v_exp_f32_e32 v249, v249
	v_pk_add_f32 v[242:243], v[242:243], 1.0 op_sel_hi:[1,0]
	v_pk_add_f32 v[244:245], v[244:245], 1.0 op_sel_hi:[1,0]
	v_pk_add_f32 v[246:247], v[246:247], 1.0 op_sel_hi:[1,0]
	v_pk_add_f32 v[248:249], v[248:249], 1.0 op_sel_hi:[1,0]
	v_rcp_f32_e32 v242, v242
	v_rcp_f32_e32 v243, v243
	v_rcp_f32_e32 v244, v244
	v_rcp_f32_e32 v245, v245
	v_rcp_f32_e32 v246, v246
	v_rcp_f32_e32 v247, v247
	v_rcp_f32_e32 v248, v248
	v_rcp_f32_e32 v249, v249
	v_fma_mix_f32 v242, v20, v242, v176 op_sel:[0,0,0] op_sel_hi:[0,0,1]
	v_fma_mix_f32 v243, v21, v243, v176 op_sel:[0,0,1] op_sel_hi:[0,0,1]
	v_fma_mix_f32 v244, v22, v244, v177 op_sel:[0,0,0] op_sel_hi:[0,0,1]
	v_fma_mix_f32 v245, v23, v245, v177 op_sel:[0,0,1] op_sel_hi:[0,0,1]
	v_fma_mix_f32 v246, v24, v246, v178 op_sel:[0,0,0] op_sel_hi:[0,0,1]
	v_fma_mix_f32 v247, v25, v247, v178 op_sel:[0,0,1] op_sel_hi:[0,0,1]
	v_fma_mix_f32 v248, v26, v248, v179 op_sel:[0,0,0] op_sel_hi:[0,0,1]
	v_fma_mix_f32 v249, v27, v249, v179 op_sel:[0,0,1] op_sel_hi:[0,0,1]
	v_cvt_pk_f16_f32 v168, v242, v243
	v_cvt_pk_f16_f32 v169, v244, v245
	v_cvt_pk_f16_f32 v170, v246, v247
	v_cvt_pk_f16_f32 v171, v248, v249
	global_store_dwordx4 v[214:215], v[168:171], off offset:256
	v_lshl_add_u64 v[214:215], v[214:215], 0, s[10:11]
	s_waitcnt vmcnt(6)
	v_fma_mix_f32 v242, v180, s5, 0 op_sel:[0,0,0] op_sel_hi:[1,0,0]
	v_fma_mix_f32 v243, v180, s5, 0 op_sel:[1,0,0] op_sel_hi:[1,0,0]
	v_fma_mix_f32 v244, v181, s5, 0 op_sel:[0,0,0] op_sel_hi:[1,0,0]
	v_fma_mix_f32 v245, v181, s5, 0 op_sel:[1,0,0] op_sel_hi:[1,0,0]
	v_fma_mix_f32 v246, v182, s5, 0 op_sel:[0,0,0] op_sel_hi:[1,0,0]
	v_fma_mix_f32 v247, v182, s5, 0 op_sel:[1,0,0] op_sel_hi:[1,0,0]
	v_fma_mix_f32 v248, v183, s5, 0 op_sel:[0,0,0] op_sel_hi:[1,0,0]
	v_fma_mix_f32 v249, v183, s5, 0 op_sel:[1,0,0] op_sel_hi:[1,0,0]
	v_exp_f32_e32 v242, v242
	v_exp_f32_e32 v243, v243
	v_exp_f32_e32 v244, v244
	v_exp_f32_e32 v245, v245
	v_exp_f32_e32 v246, v246
	v_exp_f32_e32 v247, v247
	v_exp_f32_e32 v248, v248
	v_exp_f32_e32 v249, v249
	v_pk_add_f32 v[242:243], v[242:243], 1.0 op_sel_hi:[1,0]
	v_pk_add_f32 v[244:245], v[244:245], 1.0 op_sel_hi:[1,0]
	v_pk_add_f32 v[246:247], v[246:247], 1.0 op_sel_hi:[1,0]
	v_pk_add_f32 v[248:249], v[248:249], 1.0 op_sel_hi:[1,0]
	v_rcp_f32_e32 v242, v242
	v_rcp_f32_e32 v243, v243
	v_rcp_f32_e32 v244, v244
	v_rcp_f32_e32 v245, v245
	v_rcp_f32_e32 v246, v246
	v_rcp_f32_e32 v247, v247
	v_rcp_f32_e32 v248, v248
	v_rcp_f32_e32 v249, v249
	v_fma_mix_f32 v242, v12, v242, v188 op_sel:[0,0,0] op_sel_hi:[0,0,1]
	v_fma_mix_f32 v243, v13, v243, v188 op_sel:[0,0,1] op_sel_hi:[0,0,1]
	v_fma_mix_f32 v244, v14, v244, v189 op_sel:[0,0,0] op_sel_hi:[0,0,1]
	v_fma_mix_f32 v245, v15, v245, v189 op_sel:[0,0,1] op_sel_hi:[0,0,1]
	v_fma_mix_f32 v246, v16, v246, v190 op_sel:[0,0,0] op_sel_hi:[0,0,1]
	v_fma_mix_f32 v247, v17, v247, v190 op_sel:[0,0,1] op_sel_hi:[0,0,1]
	v_fma_mix_f32 v248, v18, v248, v191 op_sel:[0,0,0] op_sel_hi:[0,0,1]
	v_fma_mix_f32 v249, v19, v249, v191 op_sel:[0,0,1] op_sel_hi:[0,0,1]
	v_cvt_pk_f16_f32 v180, v242, v243
	v_cvt_pk_f16_f32 v181, v244, v245
	v_cvt_pk_f16_f32 v182, v246, v247
	v_cvt_pk_f16_f32 v183, v248, v249
	global_store_dwordx4 v[214:215], v[180:183], off
	v_fma_mix_f32 v242, v184, s5, 0 op_sel:[0,0,0] op_sel_hi:[1,0,0]
	v_fma_mix_f32 v243, v184, s5, 0 op_sel:[1,0,0] op_sel_hi:[1,0,0]
	v_fma_mix_f32 v244, v185, s5, 0 op_sel:[0,0,0] op_sel_hi:[1,0,0]
	v_fma_mix_f32 v245, v185, s5, 0 op_sel:[1,0,0] op_sel_hi:[1,0,0]
	v_fma_mix_f32 v246, v186, s5, 0 op_sel:[0,0,0] op_sel_hi:[1,0,0]
	v_fma_mix_f32 v247, v186, s5, 0 op_sel:[1,0,0] op_sel_hi:[1,0,0]
	v_fma_mix_f32 v248, v187, s5, 0 op_sel:[0,0,0] op_sel_hi:[1,0,0]
	v_fma_mix_f32 v249, v187, s5, 0 op_sel:[1,0,0] op_sel_hi:[1,0,0]
	v_exp_f32_e32 v242, v242
	v_exp_f32_e32 v243, v243
	v_exp_f32_e32 v244, v244
	v_exp_f32_e32 v245, v245
	v_exp_f32_e32 v246, v246
	v_exp_f32_e32 v247, v247
	v_exp_f32_e32 v248, v248
	v_exp_f32_e32 v249, v249
	v_pk_add_f32 v[242:243], v[242:243], 1.0 op_sel_hi:[1,0]
	v_pk_add_f32 v[244:245], v[244:245], 1.0 op_sel_hi:[1,0]
	v_pk_add_f32 v[246:247], v[246:247], 1.0 op_sel_hi:[1,0]
	v_pk_add_f32 v[248:249], v[248:249], 1.0 op_sel_hi:[1,0]
	v_rcp_f32_e32 v242, v242
	v_rcp_f32_e32 v243, v243
	v_rcp_f32_e32 v244, v244
	v_rcp_f32_e32 v245, v245
	v_rcp_f32_e32 v246, v246
	v_rcp_f32_e32 v247, v247
	v_rcp_f32_e32 v248, v248
	v_rcp_f32_e32 v249, v249
	v_fma_mix_f32 v242, v8, v242, v192 op_sel:[0,0,0] op_sel_hi:[0,0,1]
	v_fma_mix_f32 v243, v9, v243, v192 op_sel:[0,0,1] op_sel_hi:[0,0,1]
	v_fma_mix_f32 v244, v10, v244, v193 op_sel:[0,0,0] op_sel_hi:[0,0,1]
	v_fma_mix_f32 v245, v11, v245, v193 op_sel:[0,0,1] op_sel_hi:[0,0,1]
	v_fma_mix_f32 v246, v4, v246, v194 op_sel:[0,0,0] op_sel_hi:[0,0,1]
	v_fma_mix_f32 v247, v5, v247, v194 op_sel:[0,0,1] op_sel_hi:[0,0,1]
	v_fma_mix_f32 v248, v6, v248, v195 op_sel:[0,0,0] op_sel_hi:[0,0,1]
	v_fma_mix_f32 v249, v7, v249, v195 op_sel:[0,0,1] op_sel_hi:[0,0,1]
	v_cvt_pk_f16_f32 v184, v242, v243
	v_cvt_pk_f16_f32 v185, v244, v245
	v_cvt_pk_f16_f32 v186, v246, v247
	v_cvt_pk_f16_f32 v187, v248, v249
	global_store_dwordx4 v[214:215], v[184:187], off offset:256
	s_branch .LBB0_452
.Lep13_noold:
	s_mov_b64 vcc, 0x28000
	global_load_dwordx4 v[132:135], v[210:211], off
	global_load_dwordx4 v[136:139], v[210:211], off offset:256
	v_lshl_add_u64 v[210:211], v[210:211], 0, s[2:3]
	global_load_dwordx4 v[148:151], v[210:211], off
	global_load_dwordx4 v[152:155], v[210:211], off offset:256
	v_lshl_add_u64 v[210:211], v[210:211], 0, s[2:3]
	global_load_dwordx4 v[164:167], v[210:211], off
	global_load_dwordx4 v[168:171], v[210:211], off offset:256
	v_lshl_add_u64 v[210:211], v[210:211], 0, s[2:3]
	global_load_dwordx4 v[180:183], v[210:211], off
	global_load_dwordx4 v[184:187], v[210:211], off offset:256
	v_lshl_add_u64 v[210:211], v[210:211], 0, s[56:57]
	s_waitcnt vmcnt(6)
	v_fma_mix_f32 v242, v132, s5, 0 op_sel:[0,0,0] op_sel_hi:[1,0,0]
	v_fma_mix_f32 v243, v132, s5, 0 op_sel:[1,0,0] op_sel_hi:[1,0,0]
	v_fma_mix_f32 v244, v133, s5, 0 op_sel:[0,0,0] op_sel_hi:[1,0,0]
	v_fma_mix_f32 v245, v133, s5, 0 op_sel:[1,0,0] op_sel_hi:[1,0,0]
	v_fma_mix_f32 v246, v134, s5, 0 op_sel:[0,0,0] op_sel_hi:[1,0,0]
	v_fma_mix_f32 v247, v134, s5, 0 op_sel:[1,0,0] op_sel_hi:[1,0,0]
	v_fma_mix_f32 v248, v135, s5, 0 op_sel:[0,0,0] op_sel_hi:[1,0,0]
	v_fma_mix_f32 v249, v135, s5, 0 op_sel:[1,0,0] op_sel_hi:[1,0,0]
	v_exp_f32_e32 v242, v242
	v_exp_f32_e32 v243, v243
	v_exp_f32_e32 v244, v244
	v_exp_f32_e32 v245, v245
	v_exp_f32_e32 v246, v246
	v_exp_f32_e32 v247, v247
	v_exp_f32_e32 v248, v248
	v_exp_f32_e32 v249, v249
	v_pk_add_f32 v[242:243], v[242:243], 1.0 op_sel_hi:[1,0]
	v_pk_add_f32 v[244:245], v[244:245], 1.0 op_sel_hi:[1,0]
	v_pk_add_f32 v[246:247], v[246:247], 1.0 op_sel_hi:[1,0]
	v_pk_add_f32 v[248:249], v[248:249], 1.0 op_sel_hi:[1,0]
	v_rcp_f32_e32 v242, v242
	v_rcp_f32_e32 v243, v243
	v_rcp_f32_e32 v244, v244
	v_rcp_f32_e32 v245, v245
	v_rcp_f32_e32 v246, v246
	v_rcp_f32_e32 v247, v247
	v_rcp_f32_e32 v248, v248
	v_rcp_f32_e32 v249, v249
	v_mul_f32_e32 v242, v124, v242
	v_mul_f32_e32 v243, v125, v243
	v_mul_f32_e32 v244, v126, v244
	v_mul_f32_e32 v245, v127, v245
	v_mul_f32_e32 v246, v128, v246
	v_mul_f32_e32 v247, v129, v247
	v_mul_f32_e32 v248, v130, v248
	v_mul_f32_e32 v249, v131, v249
	v_cvt_pk_f16_f32 v132, v242, v243
	v_cvt_pk_f16_f32 v133, v244, v245
	v_cvt_pk_f16_f32 v134, v246, v247
	v_cvt_pk_f16_f32 v135, v248, v249
	global_store_dwordx4 v[214:215], v[132:135], off
	v_fma_mix_f32 v242, v136, s5, 0 op_sel:[0,0,0] op_sel_hi:[1,0,0]
	v_fma_mix_f32 v243, v136, s5, 0 op_sel:[1,0,0] op_sel_hi:[1,0,0]
	v_fma_mix_f32 v244, v137, s5, 0 op_sel:[0,0,0] op_sel_hi:[1,0,0]
	v_fma_mix_f32 v245, v137, s5, 0 op_sel:[1,0,0] op_sel_hi:[1,0,0]
	v_fma_mix_f32 v246, v138, s5, 0 op_sel:[0,0,0] op_sel_hi:[1,0,0]
	v_fma_mix_f32 v247, v138, s5, 0 op_sel:[1,0,0] op_sel_hi:[1,0,0]
	v_fma_mix_f32 v248, v139, s5, 0 op_sel:[0,0,0] op_sel_hi:[1,0,0]
	v_fma_mix_f32 v249, v139, s5, 0 op_sel:[1,0,0] op_sel_hi:[1,0,0]
	v_exp_f32_e32 v242, v242
	v_exp_f32_e32 v243, v243
	v_exp_f32_e32 v244, v244
	v_exp_f32_e32 v245, v245
	v_exp_f32_e32 v246, v246
	v_exp_f32_e32 v247, v247
	v_exp_f32_e32 v248, v248
	v_exp_f32_e32 v249, v249
	v_pk_add_f32 v[242:243], v[242:243], 1.0 op_sel_hi:[1,0]
	v_pk_add_f32 v[244:245], v[244:245], 1.0 op_sel_hi:[1,0]
	v_pk_add_f32 v[246:247], v[246:247], 1.0 op_sel_hi:[1,0]
	v_pk_add_f32 v[248:249], v[248:249], 1.0 op_sel_hi:[1,0]
	v_rcp_f32_e32 v242, v242
	v_rcp_f32_e32 v243, v243
	v_rcp_f32_e32 v244, v244
	v_rcp_f32_e32 v245, v245
	v_rcp_f32_e32 v246, v246
	v_rcp_f32_e32 v247, v247
	v_rcp_f32_e32 v248, v248
	v_rcp_f32_e32 v249, v249
	v_mul_f32_e32 v242, v116, v242
	v_mul_f32_e32 v243, v117, v243
	v_mul_f32_e32 v244, v118, v244
	v_mul_f32_e32 v245, v119, v245
	v_mul_f32_e32 v246, v120, v246
	v_mul_f32_e32 v247, v121, v247
	v_mul_f32_e32 v248, v122, v248
	v_mul_f32_e32 v249, v123, v249
	v_cvt_pk_f16_f32 v136, v242, v243
	v_cvt_pk_f16_f32 v137, v244, v245
	v_cvt_pk_f16_f32 v138, v246, v247
	v_cvt_pk_f16_f32 v139, v248, v249
	global_store_dwordx4 v[214:215], v[136:139], off offset:256
	v_lshl_add_u64 v[214:215], v[214:215], 0, s[10:11]
	global_load_dwordx4 v[132:135], v[210:211], off
	global_load_dwordx4 v[136:139], v[210:211], off offset:256
	v_lshl_add_u64 v[210:211], v[210:211], 0, s[2:3]
	s_waitcnt vmcnt(8)
	v_fma_mix_f32 v242, v148, s5, 0 op_sel:[0,0,0] op_sel_hi:[1,0,0]
	v_fma_mix_f32 v243, v148, s5, 0 op_sel:[1,0,0] op_sel_hi:[1,0,0]
	v_fma_mix_f32 v244, v149, s5, 0 op_sel:[0,0,0] op_sel_hi:[1,0,0]
	v_fma_mix_f32 v245, v149, s5, 0 op_sel:[1,0,0] op_sel_hi:[1,0,0]
	v_fma_mix_f32 v246, v150, s5, 0 op_sel:[0,0,0] op_sel_hi:[1,0,0]
	v_fma_mix_f32 v247, v150, s5, 0 op_sel:[1,0,0] op_sel_hi:[1,0,0]
	v_fma_mix_f32 v248, v151, s5, 0 op_sel:[0,0,0] op_sel_hi:[1,0,0]
	v_fma_mix_f32 v249, v151, s5, 0 op_sel:[1,0,0] op_sel_hi:[1,0,0]
	v_exp_f32_e32 v242, v242
	v_exp_f32_e32 v243, v243
	v_exp_f32_e32 v244, v244
	v_exp_f32_e32 v245, v245
	v_exp_f32_e32 v246, v246
	v_exp_f32_e32 v247, v247
	v_exp_f32_e32 v248, v248
	v_exp_f32_e32 v249, v249
	v_pk_add_f32 v[242:243], v[242:243], 1.0 op_sel_hi:[1,0]
	v_pk_add_f32 v[244:245], v[244:245], 1.0 op_sel_hi:[1,0]
	v_pk_add_f32 v[246:247], v[246:247], 1.0 op_sel_hi:[1,0]
	v_pk_add_f32 v[248:249], v[248:249], 1.0 op_sel_hi:[1,0]
	v_rcp_f32_e32 v242, v242
	v_rcp_f32_e32 v243, v243
	v_rcp_f32_e32 v244, v244
	v_rcp_f32_e32 v245, v245
	v_rcp_f32_e32 v246, v246
	v_rcp_f32_e32 v247, v247
	v_rcp_f32_e32 v248, v248
	v_rcp_f32_e32 v249, v249
	v_mul_f32_e32 v242, v108, v242
	v_mul_f32_e32 v243, v109, v243
	v_mul_f32_e32 v244, v110, v244
	v_mul_f32_e32 v245, v111, v245
	v_mul_f32_e32 v246, v112, v246
	v_mul_f32_e32 v247, v113, v247
	v_mul_f32_e32 v248, v114, v248
	v_mul_f32_e32 v249, v115, v249
	v_cvt_pk_f16_f32 v148, v242, v243
	v_cvt_pk_f16_f32 v149, v244, v245
	v_cvt_pk_f16_f32 v150, v246, v247
	v_cvt_pk_f16_f32 v151, v248, v249
	global_store_dwordx4 v[214:215], v[148:151], off
	v_fma_mix_f32 v242, v152, s5, 0 op_sel:[0,0,0] op_sel_hi:[1,0,0]
	v_fma_mix_f32 v243, v152, s5, 0 op_sel:[1,0,0] op_sel_hi:[1,0,0]
	v_fma_mix_f32 v244, v153, s5, 0 op_sel:[0,0,0] op_sel_hi:[1,0,0]
	v_fma_mix_f32 v245, v153, s5, 0 op_sel:[1,0,0] op_sel_hi:[1,0,0]
	v_fma_mix_f32 v246, v154, s5, 0 op_sel:[0,0,0] op_sel_hi:[1,0,0]
	v_fma_mix_f32 v247, v154, s5, 0 op_sel:[1,0,0] op_sel_hi:[1,0,0]
	v_fma_mix_f32 v248, v155, s5, 0 op_sel:[0,0,0] op_sel_hi:[1,0,0]
	v_fma_mix_f32 v249, v155, s5, 0 op_sel:[1,0,0] op_sel_hi:[1,0,0]
	v_exp_f32_e32 v242, v242
	v_exp_f32_e32 v243, v243
	v_exp_f32_e32 v244, v244
	v_exp_f32_e32 v245, v245
	v_exp_f32_e32 v246, v246
	v_exp_f32_e32 v247, v247
	v_exp_f32_e32 v248, v248
	v_exp_f32_e32 v249, v249
	v_pk_add_f32 v[242:243], v[242:243], 1.0 op_sel_hi:[1,0]
	v_pk_add_f32 v[244:245], v[244:245], 1.0 op_sel_hi:[1,0]
	v_pk_add_f32 v[246:247], v[246:247], 1.0 op_sel_hi:[1,0]
	v_pk_add_f32 v[248:249], v[248:249], 1.0 op_sel_hi:[1,0]
	v_rcp_f32_e32 v242, v242
	v_rcp_f32_e32 v243, v243
	v_rcp_f32_e32 v244, v244
	v_rcp_f32_e32 v245, v245
	v_rcp_f32_e32 v246, v246
	v_rcp_f32_e32 v247, v247
	v_rcp_f32_e32 v248, v248
	v_rcp_f32_e32 v249, v249
	v_mul_f32_e32 v242, v100, v242
	v_mul_f32_e32 v243, v101, v243
	v_mul_f32_e32 v244, v102, v244
	v_mul_f32_e32 v245, v103, v245
	v_mul_f32_e32 v246, v104, v246
	v_mul_f32_e32 v247, v105, v247
	v_mul_f32_e32 v248, v106, v248
	v_mul_f32_e32 v249, v107, v249
	v_cvt_pk_f16_f32 v152, v242, v243
	v_cvt_pk_f16_f32 v153, v244, v245
	v_cvt_pk_f16_f32 v154, v246, v247
	v_cvt_pk_f16_f32 v155, v248, v249
	global_store_dwordx4 v[214:215], v[152:155], off offset:256
	v_lshl_add_u64 v[214:215], v[214:215], 0, s[10:11]
	global_load_dwordx4 v[148:151], v[210:211], off
	global_load_dwordx4 v[152:155], v[210:211], off offset:256
	v_lshl_add_u64 v[210:211], v[210:211], 0, s[2:3]
	s_waitcnt vmcnt(10)
	v_fma_mix_f32 v242, v164, s5, 0 op_sel:[0,0,0] op_sel_hi:[1,0,0]
	v_fma_mix_f32 v243, v164, s5, 0 op_sel:[1,0,0] op_sel_hi:[1,0,0]
	v_fma_mix_f32 v244, v165, s5, 0 op_sel:[0,0,0] op_sel_hi:[1,0,0]
	v_fma_mix_f32 v245, v165, s5, 0 op_sel:[1,0,0] op_sel_hi:[1,0,0]
	v_fma_mix_f32 v246, v166, s5, 0 op_sel:[0,0,0] op_sel_hi:[1,0,0]
	v_fma_mix_f32 v247, v166, s5, 0 op_sel:[1,0,0] op_sel_hi:[1,0,0]
	v_fma_mix_f32 v248, v167, s5, 0 op_sel:[0,0,0] op_sel_hi:[1,0,0]
	v_fma_mix_f32 v249, v167, s5, 0 op_sel:[1,0,0] op_sel_hi:[1,0,0]
	v_exp_f32_e32 v242, v242
	v_exp_f32_e32 v243, v243
	v_exp_f32_e32 v244, v244
	v_exp_f32_e32 v245, v245
	v_exp_f32_e32 v246, v246
	v_exp_f32_e32 v247, v247
	v_exp_f32_e32 v248, v248
	v_exp_f32_e32 v249, v249
	v_pk_add_f32 v[242:243], v[242:243], 1.0 op_sel_hi:[1,0]
	v_pk_add_f32 v[244:245], v[244:245], 1.0 op_sel_hi:[1,0]
	v_pk_add_f32 v[246:247], v[246:247], 1.0 op_sel_hi:[1,0]
	v_pk_add_f32 v[248:249], v[248:249], 1.0 op_sel_hi:[1,0]
	v_rcp_f32_e32 v242, v242
	v_rcp_f32_e32 v243, v243
	v_rcp_f32_e32 v244, v244
	v_rcp_f32_e32 v245, v245
	v_rcp_f32_e32 v246, v246
	v_rcp_f32_e32 v247, v247
	v_rcp_f32_e32 v248, v248
	v_rcp_f32_e32 v249, v249
	v_mul_f32_e32 v242, v92, v242
	v_mul_f32_e32 v243, v93, v243
	v_mul_f32_e32 v244, v94, v244
	v_mul_f32_e32 v245, v95, v245
	v_mul_f32_e32 v246, v96, v246
	v_mul_f32_e32 v247, v97, v247
	v_mul_f32_e32 v248, v98, v248
	v_mul_f32_e32 v249, v99, v249
	v_cvt_pk_f16_f32 v164, v242, v243
	v_cvt_pk_f16_f32 v165, v244, v245
	v_cvt_pk_f16_f32 v166, v246, v247
	v_cvt_pk_f16_f32 v167, v248, v249
	global_store_dwordx4 v[214:215], v[164:167], off
	v_fma_mix_f32 v242, v168, s5, 0 op_sel:[0,0,0] op_sel_hi:[1,0,0]
	v_fma_mix_f32 v243, v168, s5, 0 op_sel:[1,0,0] op_sel_hi:[1,0,0]
	v_fma_mix_f32 v244, v169, s5, 0 op_sel:[0,0,0] op_sel_hi:[1,0,0]
	v_fma_mix_f32 v245, v169, s5, 0 op_sel:[1,0,0] op_sel_hi:[1,0,0]
	v_fma_mix_f32 v246, v170, s5, 0 op_sel:[0,0,0] op_sel_hi:[1,0,0]
	v_fma_mix_f32 v247, v170, s5, 0 op_sel:[1,0,0] op_sel_hi:[1,0,0]
	v_fma_mix_f32 v248, v171, s5, 0 op_sel:[0,0,0] op_sel_hi:[1,0,0]
	v_fma_mix_f32 v249, v171, s5, 0 op_sel:[1,0,0] op_sel_hi:[1,0,0]
	v_exp_f32_e32 v242, v242
	v_exp_f32_e32 v243, v243
	v_exp_f32_e32 v244, v244
	v_exp_f32_e32 v245, v245
	v_exp_f32_e32 v246, v246
	v_exp_f32_e32 v247, v247
	v_exp_f32_e32 v248, v248
	v_exp_f32_e32 v249, v249
	v_pk_add_f32 v[242:243], v[242:243], 1.0 op_sel_hi:[1,0]
	v_pk_add_f32 v[244:245], v[244:245], 1.0 op_sel_hi:[1,0]
	v_pk_add_f32 v[246:247], v[246:247], 1.0 op_sel_hi:[1,0]
	v_pk_add_f32 v[248:249], v[248:249], 1.0 op_sel_hi:[1,0]
	v_rcp_f32_e32 v242, v242
	v_rcp_f32_e32 v243, v243
	v_rcp_f32_e32 v244, v244
	v_rcp_f32_e32 v245, v245
	v_rcp_f32_e32 v246, v246
	v_rcp_f32_e32 v247, v247
	v_rcp_f32_e32 v248, v248
	v_rcp_f32_e32 v249, v249
	v_mul_f32_e32 v242, v84, v242
	v_mul_f32_e32 v243, v85, v243
	v_mul_f32_e32 v244, v86, v244
	v_mul_f32_e32 v245, v87, v245
	v_mul_f32_e32 v246, v88, v246
	v_mul_f32_e32 v247, v89, v247
	v_mul_f32_e32 v248, v90, v248
	v_mul_f32_e32 v249, v91, v249
	v_cvt_pk_f16_f32 v168, v242, v243
	v_cvt_pk_f16_f32 v169, v244, v245
	v_cvt_pk_f16_f32 v170, v246, v247
	v_cvt_pk_f16_f32 v171, v248, v249
	global_store_dwordx4 v[214:215], v[168:171], off offset:256
	v_lshl_add_u64 v[214:215], v[214:215], 0, s[10:11]
	global_load_dwordx4 v[164:167], v[210:211], off
	global_load_dwordx4 v[168:171], v[210:211], off offset:256
	v_lshl_add_u64 v[210:211], v[210:211], 0, s[2:3]
	s_waitcnt vmcnt(12)
	v_fma_mix_f32 v242, v180, s5, 0 op_sel:[0,0,0] op_sel_hi:[1,0,0]
	v_fma_mix_f32 v243, v180, s5, 0 op_sel:[1,0,0] op_sel_hi:[1,0,0]
	v_fma_mix_f32 v244, v181, s5, 0 op_sel:[0,0,0] op_sel_hi:[1,0,0]
	v_fma_mix_f32 v245, v181, s5, 0 op_sel:[1,0,0] op_sel_hi:[1,0,0]
	v_fma_mix_f32 v246, v182, s5, 0 op_sel:[0,0,0] op_sel_hi:[1,0,0]
	v_fma_mix_f32 v247, v182, s5, 0 op_sel:[1,0,0] op_sel_hi:[1,0,0]
	v_fma_mix_f32 v248, v183, s5, 0 op_sel:[0,0,0] op_sel_hi:[1,0,0]
	v_fma_mix_f32 v249, v183, s5, 0 op_sel:[1,0,0] op_sel_hi:[1,0,0]
	v_exp_f32_e32 v242, v242
	v_exp_f32_e32 v243, v243
	v_exp_f32_e32 v244, v244
	v_exp_f32_e32 v245, v245
	v_exp_f32_e32 v246, v246
	v_exp_f32_e32 v247, v247
	v_exp_f32_e32 v248, v248
	v_exp_f32_e32 v249, v249
	v_pk_add_f32 v[242:243], v[242:243], 1.0 op_sel_hi:[1,0]
	v_pk_add_f32 v[244:245], v[244:245], 1.0 op_sel_hi:[1,0]
	v_pk_add_f32 v[246:247], v[246:247], 1.0 op_sel_hi:[1,0]
	v_pk_add_f32 v[248:249], v[248:249], 1.0 op_sel_hi:[1,0]
	v_rcp_f32_e32 v242, v242
	v_rcp_f32_e32 v243, v243
	v_rcp_f32_e32 v244, v244
	v_rcp_f32_e32 v245, v245
	v_rcp_f32_e32 v246, v246
	v_rcp_f32_e32 v247, v247
	v_rcp_f32_e32 v248, v248
	v_rcp_f32_e32 v249, v249
	v_mul_f32_e32 v242, v76, v242
	v_mul_f32_e32 v243, v77, v243
	v_mul_f32_e32 v244, v78, v244
	v_mul_f32_e32 v245, v79, v245
	v_mul_f32_e32 v246, v80, v246
	v_mul_f32_e32 v247, v81, v247
	v_mul_f32_e32 v248, v82, v248
	v_mul_f32_e32 v249, v83, v249
	v_cvt_pk_f16_f32 v180, v242, v243
	v_cvt_pk_f16_f32 v181, v244, v245
	v_cvt_pk_f16_f32 v182, v246, v247
	v_cvt_pk_f16_f32 v183, v248, v249
	global_store_dwordx4 v[214:215], v[180:183], off
	v_fma_mix_f32 v242, v184, s5, 0 op_sel:[0,0,0] op_sel_hi:[1,0,0]
	v_fma_mix_f32 v243, v184, s5, 0 op_sel:[1,0,0] op_sel_hi:[1,0,0]
	v_fma_mix_f32 v244, v185, s5, 0 op_sel:[0,0,0] op_sel_hi:[1,0,0]
	v_fma_mix_f32 v245, v185, s5, 0 op_sel:[1,0,0] op_sel_hi:[1,0,0]
	v_fma_mix_f32 v246, v186, s5, 0 op_sel:[0,0,0] op_sel_hi:[1,0,0]
	v_fma_mix_f32 v247, v186, s5, 0 op_sel:[1,0,0] op_sel_hi:[1,0,0]
	v_fma_mix_f32 v248, v187, s5, 0 op_sel:[0,0,0] op_sel_hi:[1,0,0]
	v_fma_mix_f32 v249, v187, s5, 0 op_sel:[1,0,0] op_sel_hi:[1,0,0]
	v_exp_f32_e32 v242, v242
	v_exp_f32_e32 v243, v243
	v_exp_f32_e32 v244, v244
	v_exp_f32_e32 v245, v245
	v_exp_f32_e32 v246, v246
	v_exp_f32_e32 v247, v247
	v_exp_f32_e32 v248, v248
	v_exp_f32_e32 v249, v249
	v_pk_add_f32 v[242:243], v[242:243], 1.0 op_sel_hi:[1,0]
	v_pk_add_f32 v[244:245], v[244:245], 1.0 op_sel_hi:[1,0]
	v_pk_add_f32 v[246:247], v[246:247], 1.0 op_sel_hi:[1,0]
	v_pk_add_f32 v[248:249], v[248:249], 1.0 op_sel_hi:[1,0]
	v_rcp_f32_e32 v242, v242
	v_rcp_f32_e32 v243, v243
	v_rcp_f32_e32 v244, v244
	v_rcp_f32_e32 v245, v245
	v_rcp_f32_e32 v246, v246
	v_rcp_f32_e32 v247, v247
	v_rcp_f32_e32 v248, v248
	v_rcp_f32_e32 v249, v249
	v_mul_f32_e32 v242, v68, v242
	v_mul_f32_e32 v243, v69, v243
	v_mul_f32_e32 v244, v70, v244
	v_mul_f32_e32 v245, v71, v245
	v_mul_f32_e32 v246, v72, v246
	v_mul_f32_e32 v247, v73, v247
	v_mul_f32_e32 v248, v74, v248
	v_mul_f32_e32 v249, v75, v249
	v_cvt_pk_f16_f32 v184, v242, v243
	v_cvt_pk_f16_f32 v185, v244, v245
	v_cvt_pk_f16_f32 v186, v246, v247
	v_cvt_pk_f16_f32 v187, v248, v249
	global_store_dwordx4 v[214:215], v[184:187], off offset:256
	v_lshl_add_u64 v[214:215], v[214:215], 0, vcc
	global_load_dwordx4 v[180:183], v[210:211], off
	global_load_dwordx4 v[184:187], v[210:211], off offset:256
	s_waitcnt vmcnt(12)
	v_fma_mix_f32 v242, v132, s5, 0 op_sel:[0,0,0] op_sel_hi:[1,0,0]
	v_fma_mix_f32 v243, v132, s5, 0 op_sel:[1,0,0] op_sel_hi:[1,0,0]
	v_fma_mix_f32 v244, v133, s5, 0 op_sel:[0,0,0] op_sel_hi:[1,0,0]
	v_fma_mix_f32 v245, v133, s5, 0 op_sel:[1,0,0] op_sel_hi:[1,0,0]
	v_fma_mix_f32 v246, v134, s5, 0 op_sel:[0,0,0] op_sel_hi:[1,0,0]
	v_fma_mix_f32 v247, v134, s5, 0 op_sel:[1,0,0] op_sel_hi:[1,0,0]
	v_fma_mix_f32 v248, v135, s5, 0 op_sel:[0,0,0] op_sel_hi:[1,0,0]
	v_fma_mix_f32 v249, v135, s5, 0 op_sel:[1,0,0] op_sel_hi:[1,0,0]
	v_exp_f32_e32 v242, v242
	v_exp_f32_e32 v243, v243
	v_exp_f32_e32 v244, v244
	v_exp_f32_e32 v245, v245
	v_exp_f32_e32 v246, v246
	v_exp_f32_e32 v247, v247
	v_exp_f32_e32 v248, v248
	v_exp_f32_e32 v249, v249
	v_pk_add_f32 v[242:243], v[242:243], 1.0 op_sel_hi:[1,0]
	v_pk_add_f32 v[244:245], v[244:245], 1.0 op_sel_hi:[1,0]
	v_pk_add_f32 v[246:247], v[246:247], 1.0 op_sel_hi:[1,0]
	v_pk_add_f32 v[248:249], v[248:249], 1.0 op_sel_hi:[1,0]
	v_rcp_f32_e32 v242, v242
	v_rcp_f32_e32 v243, v243
	v_rcp_f32_e32 v244, v244
	v_rcp_f32_e32 v245, v245
	v_rcp_f32_e32 v246, v246
	v_rcp_f32_e32 v247, v247
	v_rcp_f32_e32 v248, v248
	v_rcp_f32_e32 v249, v249
	v_mul_f32_e32 v242, v60, v242
	v_mul_f32_e32 v243, v61, v243
	v_mul_f32_e32 v244, v62, v244
	v_mul_f32_e32 v245, v63, v245
	v_mul_f32_e32 v246, v64, v246
	v_mul_f32_e32 v247, v65, v247
	v_mul_f32_e32 v248, v66, v248
	v_mul_f32_e32 v249, v67, v249
	v_cvt_pk_f16_f32 v132, v242, v243
	v_cvt_pk_f16_f32 v133, v244, v245
	v_cvt_pk_f16_f32 v134, v246, v247
	v_cvt_pk_f16_f32 v135, v248, v249
	global_store_dwordx4 v[214:215], v[132:135], off
	v_fma_mix_f32 v242, v136, s5, 0 op_sel:[0,0,0] op_sel_hi:[1,0,0]
	v_fma_mix_f32 v243, v136, s5, 0 op_sel:[1,0,0] op_sel_hi:[1,0,0]
	v_fma_mix_f32 v244, v137, s5, 0 op_sel:[0,0,0] op_sel_hi:[1,0,0]
	v_fma_mix_f32 v245, v137, s5, 0 op_sel:[1,0,0] op_sel_hi:[1,0,0]
	v_fma_mix_f32 v246, v138, s5, 0 op_sel:[0,0,0] op_sel_hi:[1,0,0]
	v_fma_mix_f32 v247, v138, s5, 0 op_sel:[1,0,0] op_sel_hi:[1,0,0]
	v_fma_mix_f32 v248, v139, s5, 0 op_sel:[0,0,0] op_sel_hi:[1,0,0]
	v_fma_mix_f32 v249, v139, s5, 0 op_sel:[1,0,0] op_sel_hi:[1,0,0]
	v_exp_f32_e32 v242, v242
	v_exp_f32_e32 v243, v243
	v_exp_f32_e32 v244, v244
	v_exp_f32_e32 v245, v245
	v_exp_f32_e32 v246, v246
	v_exp_f32_e32 v247, v247
	v_exp_f32_e32 v248, v248
	v_exp_f32_e32 v249, v249
	v_pk_add_f32 v[242:243], v[242:243], 1.0 op_sel_hi:[1,0]
	v_pk_add_f32 v[244:245], v[244:245], 1.0 op_sel_hi:[1,0]
	v_pk_add_f32 v[246:247], v[246:247], 1.0 op_sel_hi:[1,0]
	v_pk_add_f32 v[248:249], v[248:249], 1.0 op_sel_hi:[1,0]
	v_rcp_f32_e32 v242, v242
	v_rcp_f32_e32 v243, v243
	v_rcp_f32_e32 v244, v244
	v_rcp_f32_e32 v245, v245
	v_rcp_f32_e32 v246, v246
	v_rcp_f32_e32 v247, v247
	v_rcp_f32_e32 v248, v248
	v_rcp_f32_e32 v249, v249
	v_mul_f32_e32 v242, v52, v242
	v_mul_f32_e32 v243, v53, v243
	v_mul_f32_e32 v244, v54, v244
	v_mul_f32_e32 v245, v55, v245
	v_mul_f32_e32 v246, v56, v246
	v_mul_f32_e32 v247, v57, v247
	v_mul_f32_e32 v248, v58, v248
	v_mul_f32_e32 v249, v59, v249
	v_cvt_pk_f16_f32 v136, v242, v243
	v_cvt_pk_f16_f32 v137, v244, v245
	v_cvt_pk_f16_f32 v138, v246, v247
	v_cvt_pk_f16_f32 v139, v248, v249
	global_store_dwordx4 v[214:215], v[136:139], off offset:256
	v_lshl_add_u64 v[214:215], v[214:215], 0, s[10:11]
	s_waitcnt vmcnt(10)
	v_fma_mix_f32 v242, v148, s5, 0 op_sel:[0,0,0] op_sel_hi:[1,0,0]
	v_fma_mix_f32 v243, v148, s5, 0 op_sel:[1,0,0] op_sel_hi:[1,0,0]
	v_fma_mix_f32 v244, v149, s5, 0 op_sel:[0,0,0] op_sel_hi:[1,0,0]
	v_fma_mix_f32 v245, v149, s5, 0 op_sel:[1,0,0] op_sel_hi:[1,0,0]
	v_fma_mix_f32 v246, v150, s5, 0 op_sel:[0,0,0] op_sel_hi:[1,0,0]
	v_fma_mix_f32 v247, v150, s5, 0 op_sel:[1,0,0] op_sel_hi:[1,0,0]
	v_fma_mix_f32 v248, v151, s5, 0 op_sel:[0,0,0] op_sel_hi:[1,0,0]
	v_fma_mix_f32 v249, v151, s5, 0 op_sel:[1,0,0] op_sel_hi:[1,0,0]
	v_exp_f32_e32 v242, v242
	v_exp_f32_e32 v243, v243
	v_exp_f32_e32 v244, v244
	v_exp_f32_e32 v245, v245
	v_exp_f32_e32 v246, v246
	v_exp_f32_e32 v247, v247
	v_exp_f32_e32 v248, v248
	v_exp_f32_e32 v249, v249
	v_pk_add_f32 v[242:243], v[242:243], 1.0 op_sel_hi:[1,0]
	v_pk_add_f32 v[244:245], v[244:245], 1.0 op_sel_hi:[1,0]
	v_pk_add_f32 v[246:247], v[246:247], 1.0 op_sel_hi:[1,0]
	v_pk_add_f32 v[248:249], v[248:249], 1.0 op_sel_hi:[1,0]
	v_rcp_f32_e32 v242, v242
	v_rcp_f32_e32 v243, v243
	v_rcp_f32_e32 v244, v244
	v_rcp_f32_e32 v245, v245
	v_rcp_f32_e32 v246, v246
	v_rcp_f32_e32 v247, v247
	v_rcp_f32_e32 v248, v248
	v_rcp_f32_e32 v249, v249
	v_mul_f32_e32 v242, v44, v242
	v_mul_f32_e32 v243, v45, v243
	v_mul_f32_e32 v244, v46, v244
	v_mul_f32_e32 v245, v47, v245
	v_mul_f32_e32 v246, v48, v246
	v_mul_f32_e32 v247, v49, v247
	v_mul_f32_e32 v248, v50, v248
	v_mul_f32_e32 v249, v51, v249
	v_cvt_pk_f16_f32 v148, v242, v243
	v_cvt_pk_f16_f32 v149, v244, v245
	v_cvt_pk_f16_f32 v150, v246, v247
	v_cvt_pk_f16_f32 v151, v248, v249
	global_store_dwordx4 v[214:215], v[148:151], off
	v_fma_mix_f32 v242, v152, s5, 0 op_sel:[0,0,0] op_sel_hi:[1,0,0]
	v_fma_mix_f32 v243, v152, s5, 0 op_sel:[1,0,0] op_sel_hi:[1,0,0]
	v_fma_mix_f32 v244, v153, s5, 0 op_sel:[0,0,0] op_sel_hi:[1,0,0]
	v_fma_mix_f32 v245, v153, s5, 0 op_sel:[1,0,0] op_sel_hi:[1,0,0]
	v_fma_mix_f32 v246, v154, s5, 0 op_sel:[0,0,0] op_sel_hi:[1,0,0]
	v_fma_mix_f32 v247, v154, s5, 0 op_sel:[1,0,0] op_sel_hi:[1,0,0]
	v_fma_mix_f32 v248, v155, s5, 0 op_sel:[0,0,0] op_sel_hi:[1,0,0]
	v_fma_mix_f32 v249, v155, s5, 0 op_sel:[1,0,0] op_sel_hi:[1,0,0]
	v_exp_f32_e32 v242, v242
	v_exp_f32_e32 v243, v243
	v_exp_f32_e32 v244, v244
	v_exp_f32_e32 v245, v245
	v_exp_f32_e32 v246, v246
	v_exp_f32_e32 v247, v247
	v_exp_f32_e32 v248, v248
	v_exp_f32_e32 v249, v249
	v_pk_add_f32 v[242:243], v[242:243], 1.0 op_sel_hi:[1,0]
	v_pk_add_f32 v[244:245], v[244:245], 1.0 op_sel_hi:[1,0]
	v_pk_add_f32 v[246:247], v[246:247], 1.0 op_sel_hi:[1,0]
	v_pk_add_f32 v[248:249], v[248:249], 1.0 op_sel_hi:[1,0]
	v_rcp_f32_e32 v242, v242
	v_rcp_f32_e32 v243, v243
	v_rcp_f32_e32 v244, v244
	v_rcp_f32_e32 v245, v245
	v_rcp_f32_e32 v246, v246
	v_rcp_f32_e32 v247, v247
	v_rcp_f32_e32 v248, v248
	v_rcp_f32_e32 v249, v249
	v_mul_f32_e32 v242, v36, v242
	v_mul_f32_e32 v243, v37, v243
	v_mul_f32_e32 v244, v38, v244
	v_mul_f32_e32 v245, v39, v245
	v_mul_f32_e32 v246, v40, v246
	v_mul_f32_e32 v247, v41, v247
	v_mul_f32_e32 v248, v42, v248
	v_mul_f32_e32 v249, v43, v249
	v_cvt_pk_f16_f32 v152, v242, v243
	v_cvt_pk_f16_f32 v153, v244, v245
	v_cvt_pk_f16_f32 v154, v246, v247
	v_cvt_pk_f16_f32 v155, v248, v249
	global_store_dwordx4 v[214:215], v[152:155], off offset:256
	v_lshl_add_u64 v[214:215], v[214:215], 0, s[10:11]
	s_waitcnt vmcnt(8)
	v_fma_mix_f32 v242, v164, s5, 0 op_sel:[0,0,0] op_sel_hi:[1,0,0]
	v_fma_mix_f32 v243, v164, s5, 0 op_sel:[1,0,0] op_sel_hi:[1,0,0]
	v_fma_mix_f32 v244, v165, s5, 0 op_sel:[0,0,0] op_sel_hi:[1,0,0]
	v_fma_mix_f32 v245, v165, s5, 0 op_sel:[1,0,0] op_sel_hi:[1,0,0]
	v_fma_mix_f32 v246, v166, s5, 0 op_sel:[0,0,0] op_sel_hi:[1,0,0]
	v_fma_mix_f32 v247, v166, s5, 0 op_sel:[1,0,0] op_sel_hi:[1,0,0]
	v_fma_mix_f32 v248, v167, s5, 0 op_sel:[0,0,0] op_sel_hi:[1,0,0]
	v_fma_mix_f32 v249, v167, s5, 0 op_sel:[1,0,0] op_sel_hi:[1,0,0]
	v_exp_f32_e32 v242, v242
	v_exp_f32_e32 v243, v243
	v_exp_f32_e32 v244, v244
	v_exp_f32_e32 v245, v245
	v_exp_f32_e32 v246, v246
	v_exp_f32_e32 v247, v247
	v_exp_f32_e32 v248, v248
	v_exp_f32_e32 v249, v249
	v_pk_add_f32 v[242:243], v[242:243], 1.0 op_sel_hi:[1,0]
	v_pk_add_f32 v[244:245], v[244:245], 1.0 op_sel_hi:[1,0]
	v_pk_add_f32 v[246:247], v[246:247], 1.0 op_sel_hi:[1,0]
	v_pk_add_f32 v[248:249], v[248:249], 1.0 op_sel_hi:[1,0]
	v_rcp_f32_e32 v242, v242
	v_rcp_f32_e32 v243, v243
	v_rcp_f32_e32 v244, v244
	v_rcp_f32_e32 v245, v245
	v_rcp_f32_e32 v246, v246
	v_rcp_f32_e32 v247, v247
	v_rcp_f32_e32 v248, v248
	v_rcp_f32_e32 v249, v249
	v_mul_f32_e32 v242, v28, v242
	v_mul_f32_e32 v243, v29, v243
	v_mul_f32_e32 v244, v30, v244
	v_mul_f32_e32 v245, v31, v245
	v_mul_f32_e32 v246, v32, v246
	v_mul_f32_e32 v247, v33, v247
	v_mul_f32_e32 v248, v34, v248
	v_mul_f32_e32 v249, v35, v249
	v_cvt_pk_f16_f32 v164, v242, v243
	v_cvt_pk_f16_f32 v165, v244, v245
	v_cvt_pk_f16_f32 v166, v246, v247
	v_cvt_pk_f16_f32 v167, v248, v249
	global_store_dwordx4 v[214:215], v[164:167], off
	v_fma_mix_f32 v242, v168, s5, 0 op_sel:[0,0,0] op_sel_hi:[1,0,0]
	v_fma_mix_f32 v243, v168, s5, 0 op_sel:[1,0,0] op_sel_hi:[1,0,0]
	v_fma_mix_f32 v244, v169, s5, 0 op_sel:[0,0,0] op_sel_hi:[1,0,0]
	v_fma_mix_f32 v245, v169, s5, 0 op_sel:[1,0,0] op_sel_hi:[1,0,0]
	v_fma_mix_f32 v246, v170, s5, 0 op_sel:[0,0,0] op_sel_hi:[1,0,0]
	v_fma_mix_f32 v247, v170, s5, 0 op_sel:[1,0,0] op_sel_hi:[1,0,0]
	v_fma_mix_f32 v248, v171, s5, 0 op_sel:[0,0,0] op_sel_hi:[1,0,0]
	v_fma_mix_f32 v249, v171, s5, 0 op_sel:[1,0,0] op_sel_hi:[1,0,0]
	v_exp_f32_e32 v242, v242
	v_exp_f32_e32 v243, v243
	v_exp_f32_e32 v244, v244
	v_exp_f32_e32 v245, v245
	v_exp_f32_e32 v246, v246
	v_exp_f32_e32 v247, v247
	v_exp_f32_e32 v248, v248
	v_exp_f32_e32 v249, v249
	v_pk_add_f32 v[242:243], v[242:243], 1.0 op_sel_hi:[1,0]
	v_pk_add_f32 v[244:245], v[244:245], 1.0 op_sel_hi:[1,0]
	v_pk_add_f32 v[246:247], v[246:247], 1.0 op_sel_hi:[1,0]
	v_pk_add_f32 v[248:249], v[248:249], 1.0 op_sel_hi:[1,0]
	v_rcp_f32_e32 v242, v242
	v_rcp_f32_e32 v243, v243
	v_rcp_f32_e32 v244, v244
	v_rcp_f32_e32 v245, v245
	v_rcp_f32_e32 v246, v246
	v_rcp_f32_e32 v247, v247
	v_rcp_f32_e32 v248, v248
	v_rcp_f32_e32 v249, v249
	v_mul_f32_e32 v242, v20, v242
	v_mul_f32_e32 v243, v21, v243
	v_mul_f32_e32 v244, v22, v244
	v_mul_f32_e32 v245, v23, v245
	v_mul_f32_e32 v246, v24, v246
	v_mul_f32_e32 v247, v25, v247
	v_mul_f32_e32 v248, v26, v248
	v_mul_f32_e32 v249, v27, v249
	v_cvt_pk_f16_f32 v168, v242, v243
	v_cvt_pk_f16_f32 v169, v244, v245
	v_cvt_pk_f16_f32 v170, v246, v247
	v_cvt_pk_f16_f32 v171, v248, v249
	global_store_dwordx4 v[214:215], v[168:171], off offset:256
	v_lshl_add_u64 v[214:215], v[214:215], 0, s[10:11]
	s_waitcnt vmcnt(6)
	v_fma_mix_f32 v242, v180, s5, 0 op_sel:[0,0,0] op_sel_hi:[1,0,0]
	v_fma_mix_f32 v243, v180, s5, 0 op_sel:[1,0,0] op_sel_hi:[1,0,0]
	v_fma_mix_f32 v244, v181, s5, 0 op_sel:[0,0,0] op_sel_hi:[1,0,0]
	v_fma_mix_f32 v245, v181, s5, 0 op_sel:[1,0,0] op_sel_hi:[1,0,0]
	v_fma_mix_f32 v246, v182, s5, 0 op_sel:[0,0,0] op_sel_hi:[1,0,0]
	v_fma_mix_f32 v247, v182, s5, 0 op_sel:[1,0,0] op_sel_hi:[1,0,0]
	v_fma_mix_f32 v248, v183, s5, 0 op_sel:[0,0,0] op_sel_hi:[1,0,0]
	v_fma_mix_f32 v249, v183, s5, 0 op_sel:[1,0,0] op_sel_hi:[1,0,0]
	v_exp_f32_e32 v242, v242
	v_exp_f32_e32 v243, v243
	v_exp_f32_e32 v244, v244
	v_exp_f32_e32 v245, v245
	v_exp_f32_e32 v246, v246
	v_exp_f32_e32 v247, v247
	v_exp_f32_e32 v248, v248
	v_exp_f32_e32 v249, v249
	v_pk_add_f32 v[242:243], v[242:243], 1.0 op_sel_hi:[1,0]
	v_pk_add_f32 v[244:245], v[244:245], 1.0 op_sel_hi:[1,0]
	v_pk_add_f32 v[246:247], v[246:247], 1.0 op_sel_hi:[1,0]
	v_pk_add_f32 v[248:249], v[248:249], 1.0 op_sel_hi:[1,0]
	v_rcp_f32_e32 v242, v242
	v_rcp_f32_e32 v243, v243
	v_rcp_f32_e32 v244, v244
	v_rcp_f32_e32 v245, v245
	v_rcp_f32_e32 v246, v246
	v_rcp_f32_e32 v247, v247
	v_rcp_f32_e32 v248, v248
	v_rcp_f32_e32 v249, v249
	v_mul_f32_e32 v242, v12, v242
	v_mul_f32_e32 v243, v13, v243
	v_mul_f32_e32 v244, v14, v244
	v_mul_f32_e32 v245, v15, v245
	v_mul_f32_e32 v246, v16, v246
	v_mul_f32_e32 v247, v17, v247
	v_mul_f32_e32 v248, v18, v248
	v_mul_f32_e32 v249, v19, v249
	v_cvt_pk_f16_f32 v180, v242, v243
	v_cvt_pk_f16_f32 v181, v244, v245
	v_cvt_pk_f16_f32 v182, v246, v247
	v_cvt_pk_f16_f32 v183, v248, v249
	global_store_dwordx4 v[214:215], v[180:183], off
	v_fma_mix_f32 v242, v184, s5, 0 op_sel:[0,0,0] op_sel_hi:[1,0,0]
	v_fma_mix_f32 v243, v184, s5, 0 op_sel:[1,0,0] op_sel_hi:[1,0,0]
	v_fma_mix_f32 v244, v185, s5, 0 op_sel:[0,0,0] op_sel_hi:[1,0,0]
	v_fma_mix_f32 v245, v185, s5, 0 op_sel:[1,0,0] op_sel_hi:[1,0,0]
	v_fma_mix_f32 v246, v186, s5, 0 op_sel:[0,0,0] op_sel_hi:[1,0,0]
	v_fma_mix_f32 v247, v186, s5, 0 op_sel:[1,0,0] op_sel_hi:[1,0,0]
	v_fma_mix_f32 v248, v187, s5, 0 op_sel:[0,0,0] op_sel_hi:[1,0,0]
	v_fma_mix_f32 v249, v187, s5, 0 op_sel:[1,0,0] op_sel_hi:[1,0,0]
	v_exp_f32_e32 v242, v242
	v_exp_f32_e32 v243, v243
	v_exp_f32_e32 v244, v244
	v_exp_f32_e32 v245, v245
	v_exp_f32_e32 v246, v246
	v_exp_f32_e32 v247, v247
	v_exp_f32_e32 v248, v248
	v_exp_f32_e32 v249, v249
	v_pk_add_f32 v[242:243], v[242:243], 1.0 op_sel_hi:[1,0]
	v_pk_add_f32 v[244:245], v[244:245], 1.0 op_sel_hi:[1,0]
	v_pk_add_f32 v[246:247], v[246:247], 1.0 op_sel_hi:[1,0]
	v_pk_add_f32 v[248:249], v[248:249], 1.0 op_sel_hi:[1,0]
	v_rcp_f32_e32 v242, v242
	v_rcp_f32_e32 v243, v243
	v_rcp_f32_e32 v244, v244
	v_rcp_f32_e32 v245, v245
	v_rcp_f32_e32 v246, v246
	v_rcp_f32_e32 v247, v247
	v_rcp_f32_e32 v248, v248
	v_rcp_f32_e32 v249, v249
	v_mul_f32_e32 v242, v8, v242
	v_mul_f32_e32 v243, v9, v243
	v_mul_f32_e32 v244, v10, v244
	v_mul_f32_e32 v245, v11, v245
	v_mul_f32_e32 v246, v4, v246
	v_mul_f32_e32 v247, v5, v247
	v_mul_f32_e32 v248, v6, v248
	v_mul_f32_e32 v249, v7, v249
	v_cvt_pk_f16_f32 v184, v242, v243
	v_cvt_pk_f16_f32 v185, v244, v245
	v_cvt_pk_f16_f32 v186, v246, v247
	v_cvt_pk_f16_f32 v187, v248, v249
	global_store_dwordx4 v[214:215], v[184:187], off offset:256
